# static priority split in the fused GEMM K-loops: s_setprio 0 moved from loop end to right after the early barrier, so only the LDS-read+MFMA half of each K-tile runs at priority 3
# baseline (speedup 1.0000x reference)
; __device__ __forceinline__ void lds_barrier() { asm volatile("s_waitcnt lgkmcnt(0)\n\ts_barrier" ::: "memory"); }
; __device__ __forceinline__ f32x16 mfma32(bf16x8 a, bf16x8 b, f32x16 c) { return __builtin_amdgcn_mfma_f32_32x32x16_bf16(a, b, c, 0, 0, 0); }
; __device__ __forceinline__ void gemm_big(const bf16_t* __restrict__ A, long lda, const bf16_t* __restrict__ Bt, int K, f32x16 (&acc)[2][4], unsigned char* lds) {
;     ...
;     for (int kc = 0; kc < nk; ++kc) {
;         bf16x8 af[2][2], bfr[2][4];
;         af[0][0] = *(const bf16x8*)(Ac); af[0][1] = *(const bf16x8*)(Ac + 32 * GLD);
; #pragma unroll
;         for (int ni = 0; ni < 4; ++ni) bfr[0][ni] = *(const bf16x8*)(Bc + ni * 32 * GLD);
;         __builtin_amdgcn_s_setprio(3);
; #pragma unroll
;         for (int ks = 0; ks < 4; ++ks) {
;             const int cb = ks & 1, nb = cb ^ 1;
;             if (ks < 3) {
;                 af[nb][0] = *(const bf16x8*)(Ac + (ks + 1) * 16); af[nb][1] = *(const bf16x8*)(Ac + 32 * GLD + (ks + 1) * 16);
; #pragma unroll
;                 for (int ni = 0; ni < 4; ++ni) bfr[nb][ni] = *(const bf16x8*)(Bc + ni * 32 * GLD + (ks + 1) * 16);
;             }
;             __builtin_amdgcn_sched_barrier(0);
; #pragma unroll
;             for (int ni = 0; ni < 4; ++ni) { acc[0][ni] = mfma32(af[cb][0], bfr[cb][ni], acc[0][ni]); acc[1][ni] = mfma32(af[cb][1], bfr[cb][ni], acc[1][ni]); }
;             __builtin_amdgcn_sched_barrier(0);
;         }
;         __builtin_amdgcn_s_setprio(0);
;         lds_barrier();
;         if (kc + 1 < nk) {
;             lstore();
;             if (kc + 2 < nk) gload(kc + 2);
;             lds_barrier();
;         }
;     }
.LBB0_56:
	s_cmp_gt_u32 s13, 42
	s_cbranch_scc1 .Lmy_gorig_8
	ds_read_b128 v[190:193], v187
	ds_read_b128 v[194:197], v187 offset:4608
	ds_read_b128 v[198:201], v188 offset:18432
	ds_read_b128 v[202:205], v188 offset:23040
	ds_read_b128 v[206:209], v188 offset:27648
	ds_read_b128 v[210:213], v188 offset:32256
	s_setprio 3
	ds_read_b128 v[214:217], v187 offset:32
	ds_read_b128 v[218:221], v187 offset:4640
	ds_read_b128 v[224:227], v188 offset:18464
	ds_read_b128 v[234:237], v188 offset:23072
	ds_read_b128 v[238:241], v188 offset:27680
	ds_read_b128 v[242:245], v188 offset:32288
	s_waitcnt lgkmcnt(9)
	v_mfma_f32_32x32x16_bf16 v[114:129], v[190:193], v[198:201], v[114:129]
	v_mfma_f32_32x32x16_bf16 v[50:65], v[194:197], v[198:201], v[50:65]
	s_waitcnt lgkmcnt(8)
	v_mfma_f32_32x32x16_bf16 v[98:113], v[190:193], v[202:205], v[98:113]
	v_mfma_f32_32x32x16_bf16 v[34:49], v[194:197], v[202:205], v[34:49]
	s_waitcnt lgkmcnt(7)
	v_mfma_f32_32x32x16_bf16 v[82:97], v[190:193], v[206:209], v[82:97]
	v_mfma_f32_32x32x16_bf16 v[18:33], v[194:197], v[206:209], v[18:33]
	s_waitcnt lgkmcnt(6)
	v_mfma_f32_32x32x16_bf16 v[66:81], v[190:193], v[210:213], v[66:81]
	v_mfma_f32_32x32x16_bf16 v[2:17], v[194:197], v[210:213], v[2:17]
	ds_read_b128 v[190:193], v187 offset:64
	ds_read_b128 v[194:197], v187 offset:4672
	ds_read_b128 v[198:201], v188 offset:18496
	ds_read_b128 v[202:205], v188 offset:23104
	ds_read_b128 v[206:209], v188 offset:27712
	ds_read_b128 v[210:213], v188 offset:32320
	s_waitcnt lgkmcnt(9)
	v_mfma_f32_32x32x16_bf16 v[114:129], v[214:217], v[224:227], v[114:129]
	v_mfma_f32_32x32x16_bf16 v[50:65], v[218:221], v[224:227], v[50:65]
	s_waitcnt lgkmcnt(8)
	v_mfma_f32_32x32x16_bf16 v[98:113], v[214:217], v[234:237], v[98:113]
	v_mfma_f32_32x32x16_bf16 v[34:49], v[218:221], v[234:237], v[34:49]
	s_waitcnt lgkmcnt(7)
	v_mfma_f32_32x32x16_bf16 v[82:97], v[214:217], v[238:241], v[82:97]
	v_mfma_f32_32x32x16_bf16 v[18:33], v[218:221], v[238:241], v[18:33]
	s_waitcnt lgkmcnt(6)
	v_mfma_f32_32x32x16_bf16 v[66:81], v[214:217], v[242:245], v[66:81]
	v_mfma_f32_32x32x16_bf16 v[2:17], v[218:221], v[242:245], v[2:17]
	ds_read_b128 v[214:217], v187 offset:96
	ds_read_b128 v[218:221], v187 offset:4704
	ds_read_b128 v[224:227], v188 offset:18528
	ds_read_b128 v[234:237], v188 offset:23136
	ds_read_b128 v[238:241], v188 offset:27744
	ds_read_b128 v[242:245], v188 offset:32352
	s_waitcnt lgkmcnt(9)
	v_mfma_f32_32x32x16_bf16 v[114:129], v[190:193], v[198:201], v[114:129]
	v_mfma_f32_32x32x16_bf16 v[50:65], v[194:197], v[198:201], v[50:65]
	s_waitcnt lgkmcnt(0)
	s_barrier
	s_setprio 0
	s_cmpk_eq_i32 s4, 0x1500
	s_cbranch_scc1 .Lmy_gB_8
	v_mfma_f32_32x32x16_bf16 v[98:113], v[190:193], v[202:205], v[98:113]
	s_waitcnt vmcnt(9)
	ds_write_b128 v189, v[130:133]
	v_mfma_f32_32x32x16_bf16 v[34:49], v[194:197], v[202:205], v[34:49]
	ds_write_b128 v189, v[134:137] offset:4608
	v_mfma_f32_32x32x16_bf16 v[82:97], v[190:193], v[206:209], v[82:97]
	ds_write_b128 v189, v[138:141] offset:9216
	s_add_u32 vcc_lo, s4, 0x78a8000
	s_addc_u32 vcc_hi, s5, 0
	s_nop 0
	v_lshl_add_u64 v[130:131], v[184:185], 0, vcc
	global_load_dwordx4 v[130:133], v[130:131], off offset:256
	v_mfma_f32_32x32x16_bf16 v[18:33], v[194:197], v[206:209], v[18:33]
	s_waitcnt vmcnt(8)
	ds_write_b128 v189, v[142:145] offset:13824
	s_add_u32 vcc_lo, s4, 0x78d4000
	s_addc_u32 vcc_hi, s5, 0
	s_nop 0
	v_lshl_add_u64 v[134:135], v[184:185], 0, vcc
	global_load_dwordx4 v[134:137], v[134:135], off offset:256
	v_mfma_f32_32x32x16_bf16 v[66:81], v[190:193], v[210:213], v[66:81]
	ds_write_b128 v189, v[146:149] offset:18432
	s_add_u32 vcc_lo, s4, 0x7900000
	s_addc_u32 vcc_hi, s5, 0
	s_nop 0
	v_lshl_add_u64 v[138:139], v[184:185], 0, vcc
	global_load_dwordx4 v[138:141], v[138:139], off offset:256
	v_mfma_f32_32x32x16_bf16 v[2:17], v[194:197], v[210:213], v[2:17]
	s_waitcnt vmcnt(9)
	ds_write_b128 v189, v[150:153] offset:23040
	s_add_u32 vcc_lo, s4, 0x792c000
	s_addc_u32 vcc_hi, s5, 0
	s_nop 0
	v_lshl_add_u64 v[142:143], v[184:185], 0, vcc
	global_load_dwordx4 v[142:145], v[142:143], off offset:256
	v_mfma_f32_32x32x16_bf16 v[114:129], v[214:217], v[224:227], v[114:129]
	s_waitcnt vmcnt(9)
	ds_write_b128 v189, v[154:157] offset:27648
	s_add_u32 vcc_lo, s4, 0x3328000
	s_addc_u32 vcc_hi, s5, 0
	s_nop 0
	v_lshl_add_u64 v[146:147], v[182:183], 0, vcc
	global_load_dwordx4 v[146:149], v[146:147], off offset:256
	v_mfma_f32_32x32x16_bf16 v[50:65], v[218:221], v[224:227], v[50:65]
	s_waitcnt vmcnt(9)
	ds_write_b128 v189, v[158:161] offset:32256
	s_add_u32 vcc_lo, s4, 0x3354000
	s_addc_u32 vcc_hi, s5, 0
	s_nop 0
	v_lshl_add_u64 v[150:151], v[182:183], 0, vcc
	global_load_dwordx4 v[150:153], v[150:151], off offset:256
	v_mfma_f32_32x32x16_bf16 v[98:113], v[214:217], v[234:237], v[98:113]
	s_waitcnt vmcnt(9)
	ds_write_b128 v189, v[162:165] offset:36864
	s_add_u32 vcc_lo, s4, 0x3380000
	s_addc_u32 vcc_hi, s5, 0
	s_nop 0
	v_lshl_add_u64 v[154:155], v[182:183], 0, vcc
	global_load_dwordx4 v[154:157], v[154:155], off offset:256
	v_mfma_f32_32x32x16_bf16 v[34:49], v[218:221], v[234:237], v[34:49]
	s_waitcnt vmcnt(9)
	ds_write_b128 v189, v[166:169] offset:41472
	s_add_u32 vcc_lo, s4, 0x33ac000
	s_addc_u32 vcc_hi, s5, 0
	s_nop 0
	v_lshl_add_u64 v[158:159], v[182:183], 0, vcc
	global_load_dwordx4 v[158:161], v[158:159], off offset:256
	v_mfma_f32_32x32x16_bf16 v[82:97], v[214:217], v[238:241], v[82:97]
	s_waitcnt vmcnt(9)
	ds_write_b128 v189, v[170:173] offset:46080
	s_add_u32 vcc_lo, s4, 0x33d8000
	s_addc_u32 vcc_hi, s5, 0
	s_nop 0
	v_lshl_add_u64 v[162:163], v[182:183], 0, vcc
	global_load_dwordx4 v[162:165], v[162:163], off offset:256
	v_mfma_f32_32x32x16_bf16 v[18:33], v[218:221], v[238:241], v[18:33]
	s_waitcnt vmcnt(9)
	ds_write_b128 v189, v[174:177] offset:50688
	s_add_u32 vcc_lo, s4, 0x3404000
	s_addc_u32 vcc_hi, s5, 0
	s_nop 0
	v_lshl_add_u64 v[166:167], v[182:183], 0, vcc
	global_load_dwordx4 v[166:169], v[166:167], off offset:256
	v_mfma_f32_32x32x16_bf16 v[66:81], v[214:217], v[242:245], v[66:81]
	s_add_u32 vcc_lo, s4, 0x3430000
	s_addc_u32 vcc_hi, s5, 0
	s_nop 0
	v_lshl_add_u64 v[170:171], v[182:183], 0, vcc
	global_load_dwordx4 v[170:173], v[170:171], off offset:256
	v_mfma_f32_32x32x16_bf16 v[2:17], v[218:221], v[242:245], v[2:17]
	s_add_u32 vcc_lo, s4, 0x345c000
	s_addc_u32 vcc_hi, s5, 0
	s_nop 0
	v_lshl_add_u64 v[174:175], v[182:183], 0, vcc
	global_load_dwordx4 v[174:177], v[174:175], off offset:256
	s_branch .LBB0_54
; __device__ __forceinline__ void lds_barrier() { asm volatile("s_waitcnt lgkmcnt(0)\n\ts_barrier" ::: "memory"); }
; __device__ __forceinline__ f32x16 mfma32(bf16x8 a, bf16x8 b, f32x16 c) { return __builtin_amdgcn_mfma_f32_32x32x16_bf16(a, b, c, 0, 0, 0); }
; __device__ __forceinline__ void gemm_big(const bf16_t* __restrict__ A, long lda, const bf16_t* __restrict__ Bt, int K, f32x16 (&acc)[2][4], unsigned char* lds) {
;     ...
;             for (int ni = 0; ni < 4; ++ni) { acc[0][ni] = mfma32(af[cb][0], bfr[cb][ni], acc[0][ni]); acc[1][ni] = mfma32(af[cb][1], bfr[cb][ni], acc[1][ni]); }
;             __builtin_amdgcn_sched_barrier(0);
;         }
;         __builtin_amdgcn_s_setprio(0);
;         lds_barrier();
;         if (kc + 1 < nk) {
;             lstore();
;             if (kc + 2 < nk) gload(kc + 2);
;             lds_barrier();
.Lmy_gB_8:
	v_mfma_f32_32x32x16_bf16 v[98:113], v[190:193], v[202:205], v[98:113]
	s_waitcnt vmcnt(9)
	ds_write_b128 v189, v[130:133]
	v_mfma_f32_32x32x16_bf16 v[34:49], v[194:197], v[202:205], v[34:49]
	ds_write_b128 v189, v[134:137] offset:4608
	v_mfma_f32_32x32x16_bf16 v[82:97], v[190:193], v[206:209], v[82:97]
	ds_write_b128 v189, v[138:141] offset:9216
	v_mfma_f32_32x32x16_bf16 v[18:33], v[194:197], v[206:209], v[18:33]
	s_waitcnt vmcnt(7)
	ds_write_b128 v189, v[142:145] offset:13824
	v_mfma_f32_32x32x16_bf16 v[66:81], v[190:193], v[210:213], v[66:81]
	ds_write_b128 v189, v[146:149] offset:18432
	v_mfma_f32_32x32x16_bf16 v[2:17], v[194:197], v[210:213], v[2:17]
	s_waitcnt vmcnt(6)
	ds_write_b128 v189, v[150:153] offset:23040
	v_mfma_f32_32x32x16_bf16 v[114:129], v[214:217], v[224:227], v[114:129]
	s_waitcnt vmcnt(5)
	ds_write_b128 v189, v[154:157] offset:27648
	v_mfma_f32_32x32x16_bf16 v[50:65], v[218:221], v[224:227], v[50:65]
	s_waitcnt vmcnt(4)
	ds_write_b128 v189, v[158:161] offset:32256
	v_mfma_f32_32x32x16_bf16 v[98:113], v[214:217], v[234:237], v[98:113]
	s_waitcnt vmcnt(3)
	ds_write_b128 v189, v[162:165] offset:36864
	v_mfma_f32_32x32x16_bf16 v[34:49], v[218:221], v[234:237], v[34:49]
	s_waitcnt vmcnt(2)
	ds_write_b128 v189, v[166:169] offset:41472
	v_mfma_f32_32x32x16_bf16 v[82:97], v[214:217], v[238:241], v[82:97]
	s_waitcnt vmcnt(1)
	ds_write_b128 v189, v[170:173] offset:46080
	v_mfma_f32_32x32x16_bf16 v[18:33], v[218:221], v[238:241], v[18:33]
	s_waitcnt vmcnt(0)
	ds_write_b128 v189, v[174:177] offset:50688
	v_mfma_f32_32x32x16_bf16 v[66:81], v[214:217], v[242:245], v[66:81]
	v_mfma_f32_32x32x16_bf16 v[2:17], v[218:221], v[242:245], v[2:17]
	s_branch .LBB0_54

; __device__ __forceinline__ void lds_barrier() { asm volatile("s_waitcnt lgkmcnt(0)\n\ts_barrier" ::: "memory"); }
; __device__ __forceinline__ f32x16 mfma32(bf16x8 a, bf16x8 b, f32x16 c) { return __builtin_amdgcn_mfma_f32_32x32x16_bf16(a, b, c, 0, 0, 0); }
; __device__ __forceinline__ void gemm_big(const bf16_t* __restrict__ A, long lda, const bf16_t* __restrict__ Bt, int K, f32x16 (&acc)[2][4], unsigned char* lds) {
;     ...
;     for (int kc = 0; kc < nk; ++kc) {
;         bf16x8 af[2][2], bfr[2][4];
;         af[0][0] = *(const bf16x8*)(Ac); af[0][1] = *(const bf16x8*)(Ac + 32 * GLD);
; #pragma unroll
;         for (int ni = 0; ni < 4; ++ni) bfr[0][ni] = *(const bf16x8*)(Bc + ni * 32 * GLD);
;         __builtin_amdgcn_s_setprio(3);
; #pragma unroll
;         for (int ks = 0; ks < 4; ++ks) {
;             const int cb = ks & 1, nb = cb ^ 1;
;             if (ks < 3) {
;                 af[nb][0] = *(const bf16x8*)(Ac + (ks + 1) * 16); af[nb][1] = *(const bf16x8*)(Ac + 32 * GLD + (ks + 1) * 16);
; #pragma unroll
;                 for (int ni = 0; ni < 4; ++ni) bfr[nb][ni] = *(const bf16x8*)(Bc + ni * 32 * GLD + (ks + 1) * 16);
;             }
;             __builtin_amdgcn_sched_barrier(0);
; #pragma unroll
;             for (int ni = 0; ni < 4; ++ni) { acc[0][ni] = mfma32(af[cb][0], bfr[cb][ni], acc[0][ni]); acc[1][ni] = mfma32(af[cb][1], bfr[cb][ni], acc[1][ni]); }
;             __builtin_amdgcn_sched_barrier(0);
;         }
;         __builtin_amdgcn_s_setprio(0);
;         lds_barrier();
;         if (kc + 1 < nk) {
;             lstore();
;             if (kc + 2 < nk) gload(kc + 2);
;             lds_barrier();
;         }
;     }
.LBB0_67:
	s_cmp_gt_u32 s5, 14
	s_cbranch_scc1 .Lmy_gorig_7
	ds_read_b128 v[190:193], v187
	ds_read_b128 v[194:197], v187 offset:4608
	ds_read_b128 v[198:201], v188 offset:18432
	ds_read_b128 v[202:205], v188 offset:23040
	ds_read_b128 v[206:209], v188 offset:27648
	ds_read_b128 v[210:213], v188 offset:32256
	s_setprio 3
	ds_read_b128 v[214:217], v187 offset:32
	ds_read_b128 v[218:221], v187 offset:4640
	ds_read_b128 v[224:227], v188 offset:18464
	ds_read_b128 v[234:237], v188 offset:23072
	ds_read_b128 v[238:241], v188 offset:27680
	ds_read_b128 v[242:245], v188 offset:32288
	s_waitcnt lgkmcnt(9)
	v_mfma_f32_32x32x16_bf16 v[114:129], v[190:193], v[198:201], v[114:129]
	v_mfma_f32_32x32x16_bf16 v[82:97], v[194:197], v[198:201], v[82:97]
	s_waitcnt lgkmcnt(8)
	v_mfma_f32_32x32x16_bf16 v[98:113], v[190:193], v[202:205], v[98:113]
	v_mfma_f32_32x32x16_bf16 v[66:81], v[194:197], v[202:205], v[66:81]
	s_waitcnt lgkmcnt(7)
	v_mfma_f32_32x32x16_bf16 v[50:65], v[190:193], v[206:209], v[50:65]
	v_mfma_f32_32x32x16_bf16 v[18:33], v[194:197], v[206:209], v[18:33]
	s_waitcnt lgkmcnt(6)
	v_mfma_f32_32x32x16_bf16 v[34:49], v[190:193], v[210:213], v[34:49]
	v_mfma_f32_32x32x16_bf16 v[2:17], v[194:197], v[210:213], v[2:17]
	ds_read_b128 v[190:193], v187 offset:64
	ds_read_b128 v[194:197], v187 offset:4672
	ds_read_b128 v[198:201], v188 offset:18496
	ds_read_b128 v[202:205], v188 offset:23104
	ds_read_b128 v[206:209], v188 offset:27712
	ds_read_b128 v[210:213], v188 offset:32320
	s_waitcnt lgkmcnt(9)
	v_mfma_f32_32x32x16_bf16 v[114:129], v[214:217], v[224:227], v[114:129]
	v_mfma_f32_32x32x16_bf16 v[82:97], v[218:221], v[224:227], v[82:97]
	s_waitcnt lgkmcnt(8)
	v_mfma_f32_32x32x16_bf16 v[98:113], v[214:217], v[234:237], v[98:113]
	v_mfma_f32_32x32x16_bf16 v[66:81], v[218:221], v[234:237], v[66:81]
	s_waitcnt lgkmcnt(7)
	v_mfma_f32_32x32x16_bf16 v[50:65], v[214:217], v[238:241], v[50:65]
	v_mfma_f32_32x32x16_bf16 v[18:33], v[218:221], v[238:241], v[18:33]
	s_waitcnt lgkmcnt(6)
	v_mfma_f32_32x32x16_bf16 v[34:49], v[214:217], v[242:245], v[34:49]
	v_mfma_f32_32x32x16_bf16 v[2:17], v[218:221], v[242:245], v[2:17]
	ds_read_b128 v[214:217], v187 offset:96
	ds_read_b128 v[218:221], v187 offset:4704
	ds_read_b128 v[224:227], v188 offset:18528
	ds_read_b128 v[234:237], v188 offset:23136
	ds_read_b128 v[238:241], v188 offset:27744
	ds_read_b128 v[242:245], v188 offset:32352
	s_waitcnt lgkmcnt(9)
	v_mfma_f32_32x32x16_bf16 v[114:129], v[190:193], v[198:201], v[114:129]
	v_mfma_f32_32x32x16_bf16 v[82:97], v[194:197], v[198:201], v[82:97]
	s_waitcnt lgkmcnt(0)
	s_barrier
	s_setprio 0
	s_cmpk_eq_i32 s6, 0x700
	s_cbranch_scc1 .Lmy_gB_7
	v_mfma_f32_32x32x16_bf16 v[98:113], v[190:193], v[202:205], v[98:113]
	s_waitcnt vmcnt(9)
	ds_write_b128 v189, v[130:133]
	v_mfma_f32_32x32x16_bf16 v[66:81], v[194:197], v[202:205], v[66:81]
	ds_write_b128 v189, v[134:137] offset:4608
	v_mfma_f32_32x32x16_bf16 v[50:65], v[190:193], v[206:209], v[50:65]
	ds_write_b128 v189, v[138:141] offset:9216
	s_add_u32 vcc_lo, s6, 0x38a8000
	s_addc_u32 vcc_hi, s7, 0
	s_nop 0
	v_lshl_add_u64 v[130:131], v[184:185], 0, vcc
	global_load_dwordx4 v[130:133], v[130:131], off offset:256
	v_mfma_f32_32x32x16_bf16 v[18:33], v[194:197], v[206:209], v[18:33]
	s_waitcnt vmcnt(8)
	ds_write_b128 v189, v[142:145] offset:13824
	s_add_u32 vcc_lo, s6, 0x38b8000
	s_addc_u32 vcc_hi, s7, 0
	s_nop 0
	v_lshl_add_u64 v[134:135], v[184:185], 0, vcc
	global_load_dwordx4 v[134:137], v[134:135], off offset:256
	v_mfma_f32_32x32x16_bf16 v[34:49], v[190:193], v[210:213], v[34:49]
	ds_write_b128 v189, v[146:149] offset:18432
	s_add_u32 vcc_lo, s6, 0x38c8000
	s_addc_u32 vcc_hi, s7, 0
	s_nop 0
	v_lshl_add_u64 v[138:139], v[184:185], 0, vcc
	global_load_dwordx4 v[138:141], v[138:139], off offset:256
	v_mfma_f32_32x32x16_bf16 v[2:17], v[194:197], v[210:213], v[2:17]
	s_waitcnt vmcnt(9)
	ds_write_b128 v189, v[150:153] offset:23040
	s_add_u32 vcc_lo, s6, 0x38d8000
	s_addc_u32 vcc_hi, s7, 0
	s_nop 0
	v_lshl_add_u64 v[142:143], v[184:185], 0, vcc
	global_load_dwordx4 v[142:145], v[142:143], off offset:256
	v_mfma_f32_32x32x16_bf16 v[114:129], v[214:217], v[224:227], v[114:129]
	s_waitcnt vmcnt(9)
	ds_write_b128 v189, v[154:157] offset:27648
	s_add_u32 vcc_lo, s6, 0x2828000
	s_addc_u32 vcc_hi, s7, 0
	s_nop 0
	v_lshl_add_u64 v[146:147], v[182:183], 0, vcc
	global_load_dwordx4 v[146:149], v[146:147], off offset:256
	v_mfma_f32_32x32x16_bf16 v[82:97], v[218:221], v[224:227], v[82:97]
	s_waitcnt vmcnt(9)
	ds_write_b128 v189, v[158:161] offset:32256
	s_add_u32 vcc_lo, s6, 0x2838000
	s_addc_u32 vcc_hi, s7, 0
	s_nop 0
	v_lshl_add_u64 v[150:151], v[182:183], 0, vcc
	global_load_dwordx4 v[150:153], v[150:151], off offset:256
	v_mfma_f32_32x32x16_bf16 v[98:113], v[214:217], v[234:237], v[98:113]
	s_waitcnt vmcnt(9)
	ds_write_b128 v189, v[162:165] offset:36864
	s_add_u32 vcc_lo, s6, 0x2848000
	s_addc_u32 vcc_hi, s7, 0
	s_nop 0
	v_lshl_add_u64 v[154:155], v[182:183], 0, vcc
	global_load_dwordx4 v[154:157], v[154:155], off offset:256
	v_mfma_f32_32x32x16_bf16 v[66:81], v[218:221], v[234:237], v[66:81]
	s_waitcnt vmcnt(9)
	ds_write_b128 v189, v[166:169] offset:41472
	s_add_u32 vcc_lo, s6, 0x2858000
	s_addc_u32 vcc_hi, s7, 0
	s_nop 0
	v_lshl_add_u64 v[158:159], v[182:183], 0, vcc
	global_load_dwordx4 v[158:161], v[158:159], off offset:256
	v_mfma_f32_32x32x16_bf16 v[50:65], v[214:217], v[238:241], v[50:65]
	s_waitcnt vmcnt(9)
	ds_write_b128 v189, v[170:173] offset:46080
	s_add_u32 vcc_lo, s6, 0x2868000
	s_addc_u32 vcc_hi, s7, 0
	s_nop 0
	v_lshl_add_u64 v[162:163], v[182:183], 0, vcc
	global_load_dwordx4 v[162:165], v[162:163], off offset:256
	v_mfma_f32_32x32x16_bf16 v[18:33], v[218:221], v[238:241], v[18:33]
	s_waitcnt vmcnt(9)
	ds_write_b128 v189, v[174:177] offset:50688
	s_add_u32 vcc_lo, s6, 0x2878000
	s_addc_u32 vcc_hi, s7, 0
	s_nop 0
	v_lshl_add_u64 v[166:167], v[182:183], 0, vcc
	global_load_dwordx4 v[166:169], v[166:167], off offset:256
	v_mfma_f32_32x32x16_bf16 v[34:49], v[214:217], v[242:245], v[34:49]
	s_add_u32 vcc_lo, s6, 0x2888000
	s_addc_u32 vcc_hi, s7, 0
	s_nop 0
	v_lshl_add_u64 v[170:171], v[182:183], 0, vcc
	global_load_dwordx4 v[170:173], v[170:171], off offset:256
	v_mfma_f32_32x32x16_bf16 v[2:17], v[218:221], v[242:245], v[2:17]
	s_add_u32 vcc_lo, s6, 0x2898000
	s_addc_u32 vcc_hi, s7, 0
	s_nop 0
	v_lshl_add_u64 v[174:175], v[182:183], 0, vcc
	global_load_dwordx4 v[174:177], v[174:175], off offset:256
	s_branch .LBB0_65
; __device__ __forceinline__ void lds_barrier() { asm volatile("s_waitcnt lgkmcnt(0)\n\ts_barrier" ::: "memory"); }
; __device__ __forceinline__ f32x16 mfma32(bf16x8 a, bf16x8 b, f32x16 c) { return __builtin_amdgcn_mfma_f32_32x32x16_bf16(a, b, c, 0, 0, 0); }
; __device__ __forceinline__ void gemm_big(const bf16_t* __restrict__ A, long lda, const bf16_t* __restrict__ Bt, int K, f32x16 (&acc)[2][4], unsigned char* lds) {
;     ...
;             for (int ni = 0; ni < 4; ++ni) { acc[0][ni] = mfma32(af[cb][0], bfr[cb][ni], acc[0][ni]); acc[1][ni] = mfma32(af[cb][1], bfr[cb][ni], acc[1][ni]); }
;             __builtin_amdgcn_sched_barrier(0);
;         }
;         __builtin_amdgcn_s_setprio(0);
;         lds_barrier();
;         if (kc + 1 < nk) {
;             lstore();
;             if (kc + 2 < nk) gload(kc + 2);
;             lds_barrier();
.Lmy_gB_7:
	v_mfma_f32_32x32x16_bf16 v[98:113], v[190:193], v[202:205], v[98:113]
	s_waitcnt vmcnt(9)
	ds_write_b128 v189, v[130:133]
	v_mfma_f32_32x32x16_bf16 v[66:81], v[194:197], v[202:205], v[66:81]
	ds_write_b128 v189, v[134:137] offset:4608
	v_mfma_f32_32x32x16_bf16 v[50:65], v[190:193], v[206:209], v[50:65]
	ds_write_b128 v189, v[138:141] offset:9216
	v_mfma_f32_32x32x16_bf16 v[18:33], v[194:197], v[206:209], v[18:33]
	s_waitcnt vmcnt(7)
	ds_write_b128 v189, v[142:145] offset:13824
	v_mfma_f32_32x32x16_bf16 v[34:49], v[190:193], v[210:213], v[34:49]
	ds_write_b128 v189, v[146:149] offset:18432
	v_mfma_f32_32x32x16_bf16 v[2:17], v[194:197], v[210:213], v[2:17]
	s_waitcnt vmcnt(6)
	ds_write_b128 v189, v[150:153] offset:23040
	v_mfma_f32_32x32x16_bf16 v[114:129], v[214:217], v[224:227], v[114:129]
	s_waitcnt vmcnt(5)
	ds_write_b128 v189, v[154:157] offset:27648
	v_mfma_f32_32x32x16_bf16 v[82:97], v[218:221], v[224:227], v[82:97]
	s_waitcnt vmcnt(4)
	ds_write_b128 v189, v[158:161] offset:32256
	v_mfma_f32_32x32x16_bf16 v[98:113], v[214:217], v[234:237], v[98:113]
	s_waitcnt vmcnt(3)
	ds_write_b128 v189, v[162:165] offset:36864
	v_mfma_f32_32x32x16_bf16 v[66:81], v[218:221], v[234:237], v[66:81]
	s_waitcnt vmcnt(2)
	ds_write_b128 v189, v[166:169] offset:41472
	v_mfma_f32_32x32x16_bf16 v[50:65], v[214:217], v[238:241], v[50:65]
	s_waitcnt vmcnt(1)
	ds_write_b128 v189, v[170:173] offset:46080
	v_mfma_f32_32x32x16_bf16 v[18:33], v[218:221], v[238:241], v[18:33]
	s_waitcnt vmcnt(0)
	ds_write_b128 v189, v[174:177] offset:50688
	v_mfma_f32_32x32x16_bf16 v[34:49], v[214:217], v[242:245], v[34:49]
	v_mfma_f32_32x32x16_bf16 v[2:17], v[218:221], v[242:245], v[2:17]
	s_branch .LBB0_65

; __device__ __forceinline__ void lds_barrier() { asm volatile("s_waitcnt lgkmcnt(0)\n\ts_barrier" ::: "memory"); }
; __device__ __forceinline__ f32x16 mfma32(bf16x8 a, bf16x8 b, f32x16 c) { return __builtin_amdgcn_mfma_f32_32x32x16_bf16(a, b, c, 0, 0, 0); }
; __device__ __forceinline__ void gemm_big(const bf16_t* __restrict__ A, long lda, const bf16_t* __restrict__ Bt, int K, f32x16 (&acc)[2][4], unsigned char* lds) {
;     ...
;     for (int kc = 0; kc < nk; ++kc) {
;         bf16x8 af[2][2], bfr[2][4];
;         af[0][0] = *(const bf16x8*)(Ac); af[0][1] = *(const bf16x8*)(Ac + 32 * GLD);
; #pragma unroll
;         for (int ni = 0; ni < 4; ++ni) bfr[0][ni] = *(const bf16x8*)(Bc + ni * 32 * GLD);
;         __builtin_amdgcn_s_setprio(3);
; #pragma unroll
;         for (int ks = 0; ks < 4; ++ks) {
;             const int cb = ks & 1, nb = cb ^ 1;
;             if (ks < 3) {
;                 af[nb][0] = *(const bf16x8*)(Ac + (ks + 1) * 16); af[nb][1] = *(const bf16x8*)(Ac + 32 * GLD + (ks + 1) * 16);
; #pragma unroll
;                 for (int ni = 0; ni < 4; ++ni) bfr[nb][ni] = *(const bf16x8*)(Bc + ni * 32 * GLD + (ks + 1) * 16);
;             }
;             __builtin_amdgcn_sched_barrier(0);
; #pragma unroll
;             for (int ni = 0; ni < 4; ++ni) { acc[0][ni] = mfma32(af[cb][0], bfr[cb][ni], acc[0][ni]); acc[1][ni] = mfma32(af[cb][1], bfr[cb][ni], acc[1][ni]); }
;             __builtin_amdgcn_sched_barrier(0);
;         }
;         __builtin_amdgcn_s_setprio(0);
;         lds_barrier();
;         if (kc + 1 < nk) {
;             lstore();
;             if (kc + 2 < nk) gload(kc + 2);
;             lds_barrier();
;         }
;     }
.LBB0_84:
	s_cmp_gt_u32 s5, 14
	s_cbranch_scc1 .Lmy_gorig_6
	ds_read_b128 v[190:193], v187
	ds_read_b128 v[194:197], v187 offset:4608
	ds_read_b128 v[198:201], v188 offset:18432
	ds_read_b128 v[202:205], v188 offset:23040
	ds_read_b128 v[206:209], v188 offset:27648
	ds_read_b128 v[210:213], v188 offset:32256
	s_setprio 3
	ds_read_b128 v[214:217], v187 offset:32
	ds_read_b128 v[218:221], v187 offset:4640
	ds_read_b128 v[224:227], v188 offset:18464
	ds_read_b128 v[234:237], v188 offset:23072
	ds_read_b128 v[238:241], v188 offset:27680
	ds_read_b128 v[242:245], v188 offset:32288
	s_waitcnt lgkmcnt(9)
	v_mfma_f32_32x32x16_bf16 v[114:129], v[190:193], v[198:201], v[114:129]
	v_mfma_f32_32x32x16_bf16 v[50:65], v[194:197], v[198:201], v[50:65]
	s_waitcnt lgkmcnt(8)
	v_mfma_f32_32x32x16_bf16 v[98:113], v[190:193], v[202:205], v[98:113]
	v_mfma_f32_32x32x16_bf16 v[34:49], v[194:197], v[202:205], v[34:49]
	s_waitcnt lgkmcnt(7)
	v_mfma_f32_32x32x16_bf16 v[82:97], v[190:193], v[206:209], v[82:97]
	v_mfma_f32_32x32x16_bf16 v[18:33], v[194:197], v[206:209], v[18:33]
	s_waitcnt lgkmcnt(6)
	v_mfma_f32_32x32x16_bf16 v[66:81], v[190:193], v[210:213], v[66:81]
	v_mfma_f32_32x32x16_bf16 v[2:17], v[194:197], v[210:213], v[2:17]
	ds_read_b128 v[190:193], v187 offset:64
	ds_read_b128 v[194:197], v187 offset:4672
	ds_read_b128 v[198:201], v188 offset:18496
	ds_read_b128 v[202:205], v188 offset:23104
	ds_read_b128 v[206:209], v188 offset:27712
	ds_read_b128 v[210:213], v188 offset:32320
	s_waitcnt lgkmcnt(9)
	v_mfma_f32_32x32x16_bf16 v[114:129], v[214:217], v[224:227], v[114:129]
	v_mfma_f32_32x32x16_bf16 v[50:65], v[218:221], v[224:227], v[50:65]
	s_waitcnt lgkmcnt(8)
	v_mfma_f32_32x32x16_bf16 v[98:113], v[214:217], v[234:237], v[98:113]
	v_mfma_f32_32x32x16_bf16 v[34:49], v[218:221], v[234:237], v[34:49]
	s_waitcnt lgkmcnt(7)
	v_mfma_f32_32x32x16_bf16 v[82:97], v[214:217], v[238:241], v[82:97]
	v_mfma_f32_32x32x16_bf16 v[18:33], v[218:221], v[238:241], v[18:33]
	s_waitcnt lgkmcnt(6)
	v_mfma_f32_32x32x16_bf16 v[66:81], v[214:217], v[242:245], v[66:81]
	v_mfma_f32_32x32x16_bf16 v[2:17], v[218:221], v[242:245], v[2:17]
	ds_read_b128 v[214:217], v187 offset:96
	ds_read_b128 v[218:221], v187 offset:4704
	ds_read_b128 v[224:227], v188 offset:18528
	ds_read_b128 v[234:237], v188 offset:23136
	ds_read_b128 v[238:241], v188 offset:27744
	ds_read_b128 v[242:245], v188 offset:32352
	s_waitcnt lgkmcnt(9)
	v_mfma_f32_32x32x16_bf16 v[114:129], v[190:193], v[198:201], v[114:129]
	v_mfma_f32_32x32x16_bf16 v[50:65], v[194:197], v[198:201], v[50:65]
	s_waitcnt lgkmcnt(0)
	s_barrier
	s_setprio 0
	s_cmpk_eq_i32 s6, 0x700
	s_cbranch_scc1 .Lmy_gB_6
	v_mfma_f32_32x32x16_bf16 v[98:113], v[190:193], v[202:205], v[98:113]
	s_waitcnt vmcnt(9)
	ds_write_b128 v189, v[130:133]
	v_mfma_f32_32x32x16_bf16 v[34:49], v[194:197], v[202:205], v[34:49]
	ds_write_b128 v189, v[134:137] offset:4608
	v_mfma_f32_32x32x16_bf16 v[82:97], v[190:193], v[206:209], v[82:97]
	ds_write_b128 v189, v[138:141] offset:9216
	s_add_u32 vcc_lo, s6, 0x14948000
	s_addc_u32 vcc_hi, s7, 0
	s_nop 0
	v_lshl_add_u64 v[130:131], v[184:185], 0, vcc
	global_load_dwordx4 v[130:133], v[130:131], off offset:256
	v_mfma_f32_32x32x16_bf16 v[18:33], v[194:197], v[206:209], v[18:33]
	s_waitcnt vmcnt(8)
	ds_write_b128 v189, v[142:145] offset:13824
	s_add_u32 vcc_lo, s6, 0x14958000
	s_addc_u32 vcc_hi, s7, 0
	s_nop 0
	v_lshl_add_u64 v[134:135], v[184:185], 0, vcc
	global_load_dwordx4 v[134:137], v[134:135], off offset:256
	v_mfma_f32_32x32x16_bf16 v[66:81], v[190:193], v[210:213], v[66:81]
	ds_write_b128 v189, v[146:149] offset:18432
	s_add_u32 vcc_lo, s6, 0x14968000
	s_addc_u32 vcc_hi, s7, 0
	s_nop 0
	v_lshl_add_u64 v[138:139], v[184:185], 0, vcc
	global_load_dwordx4 v[138:141], v[138:139], off offset:256
	v_mfma_f32_32x32x16_bf16 v[2:17], v[194:197], v[210:213], v[2:17]
	s_waitcnt vmcnt(9)
	ds_write_b128 v189, v[150:153] offset:23040
	s_add_u32 vcc_lo, s6, 0x14978000
	s_addc_u32 vcc_hi, s7, 0
	s_nop 0
	v_lshl_add_u64 v[142:143], v[184:185], 0, vcc
	global_load_dwordx4 v[142:145], v[142:143], off offset:256
	v_mfma_f32_32x32x16_bf16 v[114:129], v[214:217], v[224:227], v[114:129]
	s_waitcnt vmcnt(9)
	ds_write_b128 v189, v[154:157] offset:27648
	s_add_u32 vcc_lo, s6, 0x2628000
	s_addc_u32 vcc_hi, s7, 0
	s_nop 0
	v_lshl_add_u64 v[146:147], v[182:183], 0, vcc
	global_load_dwordx4 v[146:149], v[146:147], off offset:256
	v_mfma_f32_32x32x16_bf16 v[50:65], v[218:221], v[224:227], v[50:65]
	s_waitcnt vmcnt(9)
	ds_write_b128 v189, v[158:161] offset:32256
	s_add_u32 vcc_lo, s6, 0x2638000
	s_addc_u32 vcc_hi, s7, 0
	s_nop 0
	v_lshl_add_u64 v[150:151], v[182:183], 0, vcc
	global_load_dwordx4 v[150:153], v[150:151], off offset:256
	v_mfma_f32_32x32x16_bf16 v[98:113], v[214:217], v[234:237], v[98:113]
	s_waitcnt vmcnt(9)
	ds_write_b128 v189, v[162:165] offset:36864
	s_add_u32 vcc_lo, s6, 0x2648000
	s_addc_u32 vcc_hi, s7, 0
	s_nop 0
	v_lshl_add_u64 v[154:155], v[182:183], 0, vcc
	global_load_dwordx4 v[154:157], v[154:155], off offset:256
	v_mfma_f32_32x32x16_bf16 v[34:49], v[218:221], v[234:237], v[34:49]
	s_waitcnt vmcnt(9)
	ds_write_b128 v189, v[166:169] offset:41472
	s_add_u32 vcc_lo, s6, 0x2658000
	s_addc_u32 vcc_hi, s7, 0
	s_nop 0
	v_lshl_add_u64 v[158:159], v[182:183], 0, vcc
	global_load_dwordx4 v[158:161], v[158:159], off offset:256
	v_mfma_f32_32x32x16_bf16 v[82:97], v[214:217], v[238:241], v[82:97]
	s_waitcnt vmcnt(9)
	ds_write_b128 v189, v[170:173] offset:46080
	s_add_u32 vcc_lo, s6, 0x2668000
	s_addc_u32 vcc_hi, s7, 0
	s_nop 0
	v_lshl_add_u64 v[162:163], v[182:183], 0, vcc
	global_load_dwordx4 v[162:165], v[162:163], off offset:256
	v_mfma_f32_32x32x16_bf16 v[18:33], v[218:221], v[238:241], v[18:33]
	s_waitcnt vmcnt(9)
	ds_write_b128 v189, v[174:177] offset:50688
	s_add_u32 vcc_lo, s6, 0x2678000
	s_addc_u32 vcc_hi, s7, 0
	s_nop 0
	v_lshl_add_u64 v[166:167], v[182:183], 0, vcc
	global_load_dwordx4 v[166:169], v[166:167], off offset:256
	v_mfma_f32_32x32x16_bf16 v[66:81], v[214:217], v[242:245], v[66:81]
	s_add_u32 vcc_lo, s6, 0x2688000
	s_addc_u32 vcc_hi, s7, 0
	s_nop 0
	v_lshl_add_u64 v[170:171], v[182:183], 0, vcc
	global_load_dwordx4 v[170:173], v[170:171], off offset:256
	v_mfma_f32_32x32x16_bf16 v[2:17], v[218:221], v[242:245], v[2:17]
	s_add_u32 vcc_lo, s6, 0x2698000
	s_addc_u32 vcc_hi, s7, 0
	s_nop 0
	v_lshl_add_u64 v[174:175], v[182:183], 0, vcc
	global_load_dwordx4 v[174:177], v[174:175], off offset:256
	s_branch .LBB0_82

; __device__ __forceinline__ void lds_barrier() { asm volatile("s_waitcnt lgkmcnt(0)\n\ts_barrier" ::: "memory"); }
; __device__ __forceinline__ f32x16 mfma32(bf16x8 a, bf16x8 b, f32x16 c) { return __builtin_amdgcn_mfma_f32_32x32x16_bf16(a, b, c, 0, 0, 0); }
; __device__ __forceinline__ void gemm_big(const bf16_t* __restrict__ A, long lda, const bf16_t* __restrict__ Bt, int K, f32x16 (&acc)[2][4], unsigned char* lds) {
;     ...
;     for (int kc = 0; kc < nk; ++kc) {
;         bf16x8 af[2][2], bfr[2][4];
;         af[0][0] = *(const bf16x8*)(Ac); af[0][1] = *(const bf16x8*)(Ac + 32 * GLD);
; #pragma unroll
;         for (int ni = 0; ni < 4; ++ni) bfr[0][ni] = *(const bf16x8*)(Bc + ni * 32 * GLD);
;         __builtin_amdgcn_s_setprio(3);
; #pragma unroll
;         for (int ks = 0; ks < 4; ++ks) {
;             const int cb = ks & 1, nb = cb ^ 1;
;             if (ks < 3) {
;                 af[nb][0] = *(const bf16x8*)(Ac + (ks + 1) * 16); af[nb][1] = *(const bf16x8*)(Ac + 32 * GLD + (ks + 1) * 16);
; #pragma unroll
;                 for (int ni = 0; ni < 4; ++ni) bfr[nb][ni] = *(const bf16x8*)(Bc + ni * 32 * GLD + (ks + 1) * 16);
;             }
;             __builtin_amdgcn_sched_barrier(0);
; #pragma unroll
;             for (int ni = 0; ni < 4; ++ni) { acc[0][ni] = mfma32(af[cb][0], bfr[cb][ni], acc[0][ni]); acc[1][ni] = mfma32(af[cb][1], bfr[cb][ni], acc[1][ni]); }
;             __builtin_amdgcn_sched_barrier(0);
;         }
;         __builtin_amdgcn_s_setprio(0);
;         lds_barrier();
;         if (kc + 1 < nk) {
;             lstore();
;             if (kc + 2 < nk) gload(kc + 2);
;             lds_barrier();
;         }
;     }
.LBB0_115:
	s_cmp_gt_u32 s5, 14
	s_cbranch_scc1 .Lmy_gorig_5
	ds_read_b128 v[190:193], v187
	ds_read_b128 v[194:197], v187 offset:4608
	ds_read_b128 v[198:201], v188 offset:18432
	ds_read_b128 v[202:205], v188 offset:23040
	ds_read_b128 v[206:209], v188 offset:27648
	ds_read_b128 v[210:213], v188 offset:32256
	s_setprio 3
	ds_read_b128 v[214:217], v187 offset:32
	ds_read_b128 v[218:221], v187 offset:4640
	ds_read_b128 v[224:227], v188 offset:18464
	ds_read_b128 v[234:237], v188 offset:23072
	ds_read_b128 v[238:241], v188 offset:27680
	ds_read_b128 v[242:245], v188 offset:32288
	s_waitcnt lgkmcnt(9)
	v_mfma_f32_32x32x16_bf16 v[114:129], v[190:193], v[198:201], v[114:129]
	v_mfma_f32_32x32x16_bf16 v[98:113], v[194:197], v[198:201], v[98:113]
	s_waitcnt lgkmcnt(8)
	v_mfma_f32_32x32x16_bf16 v[82:97], v[190:193], v[202:205], v[82:97]
	v_mfma_f32_32x32x16_bf16 v[66:81], v[194:197], v[202:205], v[66:81]
	s_waitcnt lgkmcnt(7)
	v_mfma_f32_32x32x16_bf16 v[50:65], v[190:193], v[206:209], v[50:65]
	v_mfma_f32_32x32x16_bf16 v[34:49], v[194:197], v[206:209], v[34:49]
	s_waitcnt lgkmcnt(6)
	v_mfma_f32_32x32x16_bf16 v[18:33], v[190:193], v[210:213], v[18:33]
	v_mfma_f32_32x32x16_bf16 v[2:17], v[194:197], v[210:213], v[2:17]
	ds_read_b128 v[190:193], v187 offset:64
	ds_read_b128 v[194:197], v187 offset:4672
	ds_read_b128 v[198:201], v188 offset:18496
	ds_read_b128 v[202:205], v188 offset:23104
	ds_read_b128 v[206:209], v188 offset:27712
	ds_read_b128 v[210:213], v188 offset:32320
	s_waitcnt lgkmcnt(9)
	v_mfma_f32_32x32x16_bf16 v[114:129], v[214:217], v[224:227], v[114:129]
	v_mfma_f32_32x32x16_bf16 v[98:113], v[218:221], v[224:227], v[98:113]
	s_waitcnt lgkmcnt(8)
	v_mfma_f32_32x32x16_bf16 v[82:97], v[214:217], v[234:237], v[82:97]
	v_mfma_f32_32x32x16_bf16 v[66:81], v[218:221], v[234:237], v[66:81]
	s_waitcnt lgkmcnt(7)
	v_mfma_f32_32x32x16_bf16 v[50:65], v[214:217], v[238:241], v[50:65]
	v_mfma_f32_32x32x16_bf16 v[34:49], v[218:221], v[238:241], v[34:49]
	s_waitcnt lgkmcnt(6)
	v_mfma_f32_32x32x16_bf16 v[18:33], v[214:217], v[242:245], v[18:33]
	v_mfma_f32_32x32x16_bf16 v[2:17], v[218:221], v[242:245], v[2:17]
	ds_read_b128 v[214:217], v187 offset:96
	ds_read_b128 v[218:221], v187 offset:4704
	ds_read_b128 v[224:227], v188 offset:18528
	ds_read_b128 v[234:237], v188 offset:23136
	ds_read_b128 v[238:241], v188 offset:27744
	ds_read_b128 v[242:245], v188 offset:32352
	s_waitcnt lgkmcnt(9)
	v_mfma_f32_32x32x16_bf16 v[114:129], v[190:193], v[198:201], v[114:129]
	v_mfma_f32_32x32x16_bf16 v[98:113], v[194:197], v[198:201], v[98:113]
	s_waitcnt lgkmcnt(0)
	s_barrier
	s_setprio 0
	s_cmpk_eq_i32 s6, 0x700
	s_cbranch_scc1 .Lmy_gB_5
	v_mfma_f32_32x32x16_bf16 v[82:97], v[190:193], v[202:205], v[82:97]
	s_waitcnt vmcnt(9)
	ds_write_b128 v189, v[130:133]
	v_mfma_f32_32x32x16_bf16 v[66:81], v[194:197], v[202:205], v[66:81]
	ds_write_b128 v189, v[134:137] offset:4608
	v_mfma_f32_32x32x16_bf16 v[50:65], v[190:193], v[206:209], v[50:65]
	ds_write_b128 v189, v[138:141] offset:9216
	s_add_u32 vcc_lo, s6, 0x38a8000
	s_addc_u32 vcc_hi, s7, 0
	s_nop 0
	v_lshl_add_u64 v[130:131], v[184:185], 0, vcc
	global_load_dwordx4 v[130:133], v[130:131], off offset:256
	v_mfma_f32_32x32x16_bf16 v[34:49], v[194:197], v[206:209], v[34:49]
	s_waitcnt vmcnt(8)
	ds_write_b128 v189, v[142:145] offset:13824
	s_add_u32 vcc_lo, s6, 0x38b8000
	s_addc_u32 vcc_hi, s7, 0
	s_nop 0
	v_lshl_add_u64 v[134:135], v[184:185], 0, vcc
	global_load_dwordx4 v[134:137], v[134:135], off offset:256
	v_mfma_f32_32x32x16_bf16 v[18:33], v[190:193], v[210:213], v[18:33]
	ds_write_b128 v189, v[146:149] offset:18432
	s_add_u32 vcc_lo, s6, 0x38c8000
	s_addc_u32 vcc_hi, s7, 0
	s_nop 0
	v_lshl_add_u64 v[138:139], v[184:185], 0, vcc
	global_load_dwordx4 v[138:141], v[138:139], off offset:256
	v_mfma_f32_32x32x16_bf16 v[2:17], v[194:197], v[210:213], v[2:17]
	s_waitcnt vmcnt(9)
	ds_write_b128 v189, v[150:153] offset:23040
	s_add_u32 vcc_lo, s6, 0x38d8000
	s_addc_u32 vcc_hi, s7, 0
	s_nop 0
	v_lshl_add_u64 v[142:143], v[184:185], 0, vcc
	global_load_dwordx4 v[142:145], v[142:143], off offset:256
	v_mfma_f32_32x32x16_bf16 v[114:129], v[214:217], v[224:227], v[114:129]
	s_waitcnt vmcnt(9)
	ds_write_b128 v189, v[154:157] offset:27648
	s_add_u32 vcc_lo, s6, 0x1c88000
	s_addc_u32 vcc_hi, s7, 0
	s_nop 0
	v_lshl_add_u64 v[146:147], v[182:183], 0, vcc
	global_load_dwordx4 v[146:149], v[146:147], off offset:256
	v_mfma_f32_32x32x16_bf16 v[98:113], v[218:221], v[224:227], v[98:113]
	s_waitcnt vmcnt(9)
	ds_write_b128 v189, v[158:161] offset:32256
	s_add_u32 vcc_lo, s6, 0x1c98000
	s_addc_u32 vcc_hi, s7, 0
	s_nop 0
	v_lshl_add_u64 v[150:151], v[182:183], 0, vcc
	global_load_dwordx4 v[150:153], v[150:151], off offset:256
	v_mfma_f32_32x32x16_bf16 v[82:97], v[214:217], v[234:237], v[82:97]
	s_waitcnt vmcnt(9)
	ds_write_b128 v189, v[162:165] offset:36864
	s_add_u32 vcc_lo, s6, 0x1ca8000
	s_addc_u32 vcc_hi, s7, 0
	s_nop 0
	v_lshl_add_u64 v[154:155], v[182:183], 0, vcc
	global_load_dwordx4 v[154:157], v[154:155], off offset:256
	v_mfma_f32_32x32x16_bf16 v[66:81], v[218:221], v[234:237], v[66:81]
	s_waitcnt vmcnt(9)
	ds_write_b128 v189, v[166:169] offset:41472
	s_add_u32 vcc_lo, s6, 0x1cb8000
	s_addc_u32 vcc_hi, s7, 0
	s_nop 0
	v_lshl_add_u64 v[158:159], v[182:183], 0, vcc
	global_load_dwordx4 v[158:161], v[158:159], off offset:256
	v_mfma_f32_32x32x16_bf16 v[50:65], v[214:217], v[238:241], v[50:65]
	s_waitcnt vmcnt(9)
	ds_write_b128 v189, v[170:173] offset:46080
	s_add_u32 vcc_lo, s6, 0x1cc8000
	s_addc_u32 vcc_hi, s7, 0
	s_nop 0
	v_lshl_add_u64 v[162:163], v[182:183], 0, vcc
	global_load_dwordx4 v[162:165], v[162:163], off offset:256
	v_mfma_f32_32x32x16_bf16 v[34:49], v[218:221], v[238:241], v[34:49]
	s_waitcnt vmcnt(9)
	ds_write_b128 v189, v[174:177] offset:50688
	s_add_u32 vcc_lo, s6, 0x1cd8000
	s_addc_u32 vcc_hi, s7, 0
	s_nop 0
	v_lshl_add_u64 v[166:167], v[182:183], 0, vcc
	global_load_dwordx4 v[166:169], v[166:167], off offset:256
	v_mfma_f32_32x32x16_bf16 v[18:33], v[214:217], v[242:245], v[18:33]
	s_add_u32 vcc_lo, s6, 0x1ce8000
	s_addc_u32 vcc_hi, s7, 0
	s_nop 0
	v_lshl_add_u64 v[170:171], v[182:183], 0, vcc
	global_load_dwordx4 v[170:173], v[170:171], off offset:256
	v_mfma_f32_32x32x16_bf16 v[2:17], v[218:221], v[242:245], v[2:17]
	s_add_u32 vcc_lo, s6, 0x1cf8000
	s_addc_u32 vcc_hi, s7, 0
	s_nop 0
	v_lshl_add_u64 v[174:175], v[182:183], 0, vcc
	global_load_dwordx4 v[174:177], v[174:175], off offset:256
	s_branch .LBB0_113
; __device__ __forceinline__ void lds_barrier() { asm volatile("s_waitcnt lgkmcnt(0)\n\ts_barrier" ::: "memory"); }
; __device__ __forceinline__ void gemm_big(const bf16_t* __restrict__ A, long lda, const bf16_t* __restrict__ Bt, int K, f32x16 (&acc)[2][4], unsigned char* lds) {
;     ...
;         lds_barrier();
;         if (kc + 1 < nk) {
;             lstore();
;             if (kc + 2 < nk) gload(kc + 2);
;             lds_barrier();
.Lmy_gB_5:
	v_mfma_f32_32x32x16_bf16 v[82:97], v[190:193], v[202:205], v[82:97]
	s_waitcnt vmcnt(9)
	ds_write_b128 v189, v[130:133]
	v_mfma_f32_32x32x16_bf16 v[66:81], v[194:197], v[202:205], v[66:81]
	ds_write_b128 v189, v[134:137] offset:4608
	v_mfma_f32_32x32x16_bf16 v[50:65], v[190:193], v[206:209], v[50:65]
	ds_write_b128 v189, v[138:141] offset:9216
	v_mfma_f32_32x32x16_bf16 v[34:49], v[194:197], v[206:209], v[34:49]
	s_waitcnt vmcnt(7)
	ds_write_b128 v189, v[142:145] offset:13824
	v_mfma_f32_32x32x16_bf16 v[18:33], v[190:193], v[210:213], v[18:33]
	ds_write_b128 v189, v[146:149] offset:18432
	v_mfma_f32_32x32x16_bf16 v[2:17], v[194:197], v[210:213], v[2:17]
	s_waitcnt vmcnt(6)
	ds_write_b128 v189, v[150:153] offset:23040
	v_mfma_f32_32x32x16_bf16 v[114:129], v[214:217], v[224:227], v[114:129]
	s_waitcnt vmcnt(5)
	ds_write_b128 v189, v[154:157] offset:27648
	v_mfma_f32_32x32x16_bf16 v[98:113], v[218:221], v[224:227], v[98:113]
	s_waitcnt vmcnt(4)
	ds_write_b128 v189, v[158:161] offset:32256
	v_mfma_f32_32x32x16_bf16 v[82:97], v[214:217], v[234:237], v[82:97]
	s_waitcnt vmcnt(3)
	ds_write_b128 v189, v[162:165] offset:36864
	v_mfma_f32_32x32x16_bf16 v[66:81], v[218:221], v[234:237], v[66:81]
	s_waitcnt vmcnt(2)
	ds_write_b128 v189, v[166:169] offset:41472
	v_mfma_f32_32x32x16_bf16 v[50:65], v[214:217], v[238:241], v[50:65]
	s_waitcnt vmcnt(1)
	ds_write_b128 v189, v[170:173] offset:46080
	v_mfma_f32_32x32x16_bf16 v[34:49], v[218:221], v[238:241], v[34:49]
	s_waitcnt vmcnt(0)
	ds_write_b128 v189, v[174:177] offset:50688
	v_mfma_f32_32x32x16_bf16 v[18:33], v[214:217], v[242:245], v[18:33]
	v_mfma_f32_32x32x16_bf16 v[2:17], v[218:221], v[242:245], v[2:17]
	s_branch .LBB0_113

; __device__ __forceinline__ void lds_barrier() { asm volatile("s_waitcnt lgkmcnt(0)\n\ts_barrier" ::: "memory"); }
; __device__ __forceinline__ f32x16 mfma32(bf16x8 a, bf16x8 b, f32x16 c) { return __builtin_amdgcn_mfma_f32_32x32x16_bf16(a, b, c, 0, 0, 0); }
; __device__ __forceinline__ void gemm_big(const bf16_t* __restrict__ A, long lda, const bf16_t* __restrict__ Bt, int K, f32x16 (&acc)[2][4], unsigned char* lds) {
;     ...
;     for (int kc = 0; kc < nk; ++kc) {
;         bf16x8 af[2][2], bfr[2][4];
;         af[0][0] = *(const bf16x8*)(Ac); af[0][1] = *(const bf16x8*)(Ac + 32 * GLD);
; #pragma unroll
;         for (int ni = 0; ni < 4; ++ni) bfr[0][ni] = *(const bf16x8*)(Bc + ni * 32 * GLD);
;         __builtin_amdgcn_s_setprio(3);
; #pragma unroll
;         for (int ks = 0; ks < 4; ++ks) {
;             const int cb = ks & 1, nb = cb ^ 1;
;             if (ks < 3) {
;                 af[nb][0] = *(const bf16x8*)(Ac + (ks + 1) * 16); af[nb][1] = *(const bf16x8*)(Ac + 32 * GLD + (ks + 1) * 16);
; #pragma unroll
;                 for (int ni = 0; ni < 4; ++ni) bfr[nb][ni] = *(const bf16x8*)(Bc + ni * 32 * GLD + (ks + 1) * 16);
;             }
;             __builtin_amdgcn_sched_barrier(0);
; #pragma unroll
;             for (int ni = 0; ni < 4; ++ni) { acc[0][ni] = mfma32(af[cb][0], bfr[cb][ni], acc[0][ni]); acc[1][ni] = mfma32(af[cb][1], bfr[cb][ni], acc[1][ni]); }
;             __builtin_amdgcn_sched_barrier(0);
;         }
;         __builtin_amdgcn_s_setprio(0);
;         lds_barrier();
;         if (kc + 1 < nk) {
;             lstore();
;             if (kc + 2 < nk) gload(kc + 2);
;             lds_barrier();
;         }
;     }
; __device__ __forceinline__ void mla_up_tile(const Params& p, int b, int it, unsigned char* lds) {
;     ...
;         const int pn = it % 3, pm = it / 3;
;         gemm_big(PB + (size_t)pm * 128 * PBW + PB_CQ, PBW, wb + W_UQ + (size_t)pn * 256 * 256, 256, acc, lds);
.LBB0_283:
	s_cmp_gt_u32 s5, 2
	s_cbranch_scc1 .Lmy_gorig_3
	ds_read_b128 v[192:195], v189
	ds_read_b128 v[196:199], v189 offset:4608
	ds_read_b128 v[200:203], v190 offset:18432
	ds_read_b128 v[204:207], v190 offset:23040
	ds_read_b128 v[208:211], v190 offset:27648
	ds_read_b128 v[212:215], v190 offset:32256
	s_setprio 3
	ds_read_b128 v[216:219], v189 offset:32
	ds_read_b128 v[224:227], v189 offset:4640
	ds_read_b128 v[234:237], v190 offset:18464
	ds_read_b128 v[238:241], v190 offset:23072
	ds_read_b128 v[242:245], v190 offset:27680
	ds_read_b128 v[246:249], v190 offset:32288
	s_waitcnt lgkmcnt(9)
	v_mfma_f32_32x32x16_bf16 v[114:129], v[192:195], v[200:203], v[114:129]
	v_mfma_f32_32x32x16_bf16 v[50:65], v[196:199], v[200:203], v[50:65]
	s_waitcnt lgkmcnt(8)
	v_mfma_f32_32x32x16_bf16 v[98:113], v[192:195], v[204:207], v[98:113]
	v_mfma_f32_32x32x16_bf16 v[34:49], v[196:199], v[204:207], v[34:49]
	s_waitcnt lgkmcnt(7)
	v_mfma_f32_32x32x16_bf16 v[82:97], v[192:195], v[208:211], v[82:97]
	v_mfma_f32_32x32x16_bf16 v[18:33], v[196:199], v[208:211], v[18:33]
	s_waitcnt lgkmcnt(6)
	v_mfma_f32_32x32x16_bf16 v[66:81], v[192:195], v[212:215], v[66:81]
	v_mfma_f32_32x32x16_bf16 v[2:17], v[196:199], v[212:215], v[2:17]
	ds_read_b128 v[192:195], v189 offset:64
	ds_read_b128 v[196:199], v189 offset:4672
	ds_read_b128 v[200:203], v190 offset:18496
	ds_read_b128 v[204:207], v190 offset:23104
	ds_read_b128 v[208:211], v190 offset:27712
	ds_read_b128 v[212:215], v190 offset:32320
	s_waitcnt lgkmcnt(9)
	v_mfma_f32_32x32x16_bf16 v[114:129], v[216:219], v[234:237], v[114:129]
	v_mfma_f32_32x32x16_bf16 v[50:65], v[224:227], v[234:237], v[50:65]
	s_waitcnt lgkmcnt(8)
	v_mfma_f32_32x32x16_bf16 v[98:113], v[216:219], v[238:241], v[98:113]
	v_mfma_f32_32x32x16_bf16 v[34:49], v[224:227], v[238:241], v[34:49]
	s_waitcnt lgkmcnt(7)
	v_mfma_f32_32x32x16_bf16 v[82:97], v[216:219], v[242:245], v[82:97]
	v_mfma_f32_32x32x16_bf16 v[18:33], v[224:227], v[242:245], v[18:33]
	s_waitcnt lgkmcnt(6)
	v_mfma_f32_32x32x16_bf16 v[66:81], v[216:219], v[246:249], v[66:81]
	v_mfma_f32_32x32x16_bf16 v[2:17], v[224:227], v[246:249], v[2:17]
	ds_read_b128 v[216:219], v189 offset:96
	ds_read_b128 v[224:227], v189 offset:4704
	ds_read_b128 v[234:237], v190 offset:18528
	ds_read_b128 v[238:241], v190 offset:23136
	ds_read_b128 v[242:245], v190 offset:27744
	ds_read_b128 v[246:249], v190 offset:32352
	s_waitcnt lgkmcnt(9)
	v_mfma_f32_32x32x16_bf16 v[114:129], v[192:195], v[200:203], v[114:129]
	v_mfma_f32_32x32x16_bf16 v[50:65], v[196:199], v[200:203], v[50:65]
	s_waitcnt lgkmcnt(0)
	s_barrier
	s_setprio 0
	s_cmpk_eq_i32 s6, 0x100
	s_cbranch_scc1 .Lmy_gB_3
	v_mfma_f32_32x32x16_bf16 v[98:113], v[192:195], v[204:207], v[98:113]
	s_waitcnt vmcnt(9)
	ds_write_b128 v191, v[130:133]
	v_mfma_f32_32x32x16_bf16 v[34:49], v[196:199], v[204:207], v[34:49]
	ds_write_b128 v191, v[134:137] offset:4608
	v_mfma_f32_32x32x16_bf16 v[82:97], v[192:195], v[208:211], v[82:97]
	ds_write_b128 v191, v[138:141] offset:9216
	s_add_u32 vcc_lo, s6, 0x78a8000
	s_addc_u32 vcc_hi, s7, 0
	s_nop 0
	v_lshl_add_u64 v[130:131], v[184:185], 0, vcc
	global_load_dwordx4 v[130:133], v[130:131], off offset:3328
	v_mfma_f32_32x32x16_bf16 v[18:33], v[196:199], v[208:211], v[18:33]
	s_waitcnt vmcnt(8)
	ds_write_b128 v191, v[142:145] offset:13824
	s_add_u32 vcc_lo, s6, 0x78e6000
	s_addc_u32 vcc_hi, s7, 0
	s_nop 0
	v_lshl_add_u64 v[134:135], v[184:185], 0, vcc
	global_load_dwordx4 v[134:137], v[134:135], off offset:3328
	v_mfma_f32_32x32x16_bf16 v[66:81], v[192:195], v[212:215], v[66:81]
	ds_write_b128 v191, v[146:149] offset:18432
	s_add_u32 vcc_lo, s6, 0x7924000
	s_addc_u32 vcc_hi, s7, 0
	s_nop 0
	v_lshl_add_u64 v[138:139], v[184:185], 0, vcc
	global_load_dwordx4 v[138:141], v[138:139], off offset:3328
	v_mfma_f32_32x32x16_bf16 v[2:17], v[196:199], v[212:215], v[2:17]
	s_waitcnt vmcnt(9)
	ds_write_b128 v191, v[150:153] offset:23040
	s_add_u32 vcc_lo, s6, 0x7962000
	s_addc_u32 vcc_hi, s7, 0
	s_nop 0
	v_lshl_add_u64 v[142:143], v[184:185], 0, vcc
	global_load_dwordx4 v[142:145], v[142:143], off offset:3328
	v_mfma_f32_32x32x16_bf16 v[114:129], v[216:219], v[234:237], v[114:129]
	s_waitcnt vmcnt(9)
	ds_write_b128 v191, v[154:157] offset:27648
	s_add_u32 vcc_lo, s6, 0x2288000
	s_addc_u32 vcc_hi, s7, 0
	s_nop 0
	v_lshl_add_u64 v[146:147], v[182:183], 0, vcc
	global_load_dwordx4 v[146:149], v[146:147], off offset:256
	v_mfma_f32_32x32x16_bf16 v[50:65], v[224:227], v[234:237], v[50:65]
	s_waitcnt vmcnt(9)
	ds_write_b128 v191, v[158:161] offset:32256
	s_add_u32 vcc_lo, s6, 0x228c000
	s_addc_u32 vcc_hi, s7, 0
	s_nop 0
	v_lshl_add_u64 v[150:151], v[182:183], 0, vcc
	global_load_dwordx4 v[150:153], v[150:151], off offset:256
	v_mfma_f32_32x32x16_bf16 v[98:113], v[216:219], v[238:241], v[98:113]
	s_waitcnt vmcnt(9)
	ds_write_b128 v191, v[162:165] offset:36864
	s_add_u32 vcc_lo, s6, 0x2290000
	s_addc_u32 vcc_hi, s7, 0
	s_nop 0
	v_lshl_add_u64 v[154:155], v[182:183], 0, vcc
	global_load_dwordx4 v[154:157], v[154:155], off offset:256
	v_mfma_f32_32x32x16_bf16 v[34:49], v[224:227], v[238:241], v[34:49]
	s_waitcnt vmcnt(9)
	ds_write_b128 v191, v[166:169] offset:41472
	s_add_u32 vcc_lo, s6, 0x2294000
	s_addc_u32 vcc_hi, s7, 0
	s_nop 0
	v_lshl_add_u64 v[158:159], v[182:183], 0, vcc
	global_load_dwordx4 v[158:161], v[158:159], off offset:256
	v_mfma_f32_32x32x16_bf16 v[82:97], v[216:219], v[242:245], v[82:97]
	s_waitcnt vmcnt(9)
	ds_write_b128 v191, v[170:173] offset:46080
	s_add_u32 vcc_lo, s6, 0x2298000
	s_addc_u32 vcc_hi, s7, 0
	s_nop 0
	v_lshl_add_u64 v[162:163], v[182:183], 0, vcc
	global_load_dwordx4 v[162:165], v[162:163], off offset:256
	v_mfma_f32_32x32x16_bf16 v[18:33], v[224:227], v[242:245], v[18:33]
	s_waitcnt vmcnt(9)
	ds_write_b128 v191, v[174:177] offset:50688
	s_add_u32 vcc_lo, s6, 0x229c000
	s_addc_u32 vcc_hi, s7, 0
	s_nop 0
	v_lshl_add_u64 v[166:167], v[182:183], 0, vcc
	global_load_dwordx4 v[166:169], v[166:167], off offset:256
	v_mfma_f32_32x32x16_bf16 v[66:81], v[216:219], v[246:249], v[66:81]
	s_add_u32 vcc_lo, s6, 0x22a0000
	s_addc_u32 vcc_hi, s7, 0
	s_nop 0
	v_lshl_add_u64 v[170:171], v[182:183], 0, vcc
	global_load_dwordx4 v[170:173], v[170:171], off offset:256
	v_mfma_f32_32x32x16_bf16 v[2:17], v[224:227], v[246:249], v[2:17]
	s_add_u32 vcc_lo, s6, 0x22a4000
	s_addc_u32 vcc_hi, s7, 0
	s_nop 0
	v_lshl_add_u64 v[174:175], v[182:183], 0, vcc
	global_load_dwordx4 v[174:177], v[174:175], off offset:256
	s_branch .LBB0_281
; __device__ __forceinline__ void lds_barrier() { asm volatile("s_waitcnt lgkmcnt(0)\n\ts_barrier" ::: "memory"); }
; __device__ __forceinline__ void gemm_big(const bf16_t* __restrict__ A, long lda, const bf16_t* __restrict__ Bt, int K, f32x16 (&acc)[2][4], unsigned char* lds) {
;     ...
;         lds_barrier();
;         if (kc + 1 < nk) {
;             lstore();
;             if (kc + 2 < nk) gload(kc + 2);
;             lds_barrier();
.Lmy_gB_3:
	v_mfma_f32_32x32x16_bf16 v[98:113], v[192:195], v[204:207], v[98:113]
	s_waitcnt vmcnt(9)
	ds_write_b128 v191, v[130:133]
	v_mfma_f32_32x32x16_bf16 v[34:49], v[196:199], v[204:207], v[34:49]
	ds_write_b128 v191, v[134:137] offset:4608
	v_mfma_f32_32x32x16_bf16 v[82:97], v[192:195], v[208:211], v[82:97]
	ds_write_b128 v191, v[138:141] offset:9216
	v_mfma_f32_32x32x16_bf16 v[18:33], v[196:199], v[208:211], v[18:33]
	s_waitcnt vmcnt(7)
	ds_write_b128 v191, v[142:145] offset:13824
	v_mfma_f32_32x32x16_bf16 v[66:81], v[192:195], v[212:215], v[66:81]
	ds_write_b128 v191, v[146:149] offset:18432
	v_mfma_f32_32x32x16_bf16 v[2:17], v[196:199], v[212:215], v[2:17]
	s_waitcnt vmcnt(6)
	ds_write_b128 v191, v[150:153] offset:23040
	v_mfma_f32_32x32x16_bf16 v[114:129], v[216:219], v[234:237], v[114:129]
	s_waitcnt vmcnt(5)
	ds_write_b128 v191, v[154:157] offset:27648
	v_mfma_f32_32x32x16_bf16 v[50:65], v[224:227], v[234:237], v[50:65]
	s_waitcnt vmcnt(4)
	ds_write_b128 v191, v[158:161] offset:32256
	v_mfma_f32_32x32x16_bf16 v[98:113], v[216:219], v[238:241], v[98:113]
	s_waitcnt vmcnt(3)
	ds_write_b128 v191, v[162:165] offset:36864
	v_mfma_f32_32x32x16_bf16 v[34:49], v[224:227], v[238:241], v[34:49]
	s_waitcnt vmcnt(2)
	ds_write_b128 v191, v[166:169] offset:41472
	v_mfma_f32_32x32x16_bf16 v[82:97], v[216:219], v[242:245], v[82:97]
	s_waitcnt vmcnt(1)
	ds_write_b128 v191, v[170:173] offset:46080
	v_mfma_f32_32x32x16_bf16 v[18:33], v[224:227], v[242:245], v[18:33]
	s_waitcnt vmcnt(0)
	ds_write_b128 v191, v[174:177] offset:50688
	v_mfma_f32_32x32x16_bf16 v[66:81], v[216:219], v[246:249], v[66:81]
	v_mfma_f32_32x32x16_bf16 v[2:17], v[224:227], v[246:249], v[2:17]
	s_branch .LBB0_281

; __device__ __forceinline__ void lds_barrier() { asm volatile("s_waitcnt lgkmcnt(0)\n\ts_barrier" ::: "memory"); }
; __device__ __forceinline__ f32x16 mfma32(bf16x8 a, bf16x8 b, f32x16 c) { return __builtin_amdgcn_mfma_f32_32x32x16_bf16(a, b, c, 0, 0, 0); }
; __device__ __forceinline__ void gemm_big(const bf16_t* __restrict__ A, long lda, const bf16_t* __restrict__ Bt, int K, f32x16 (&acc)[2][4], unsigned char* lds) {
;     ...
;     for (int kc = 0; kc < nk; ++kc) {
;         bf16x8 af[2][2], bfr[2][4];
;         af[0][0] = *(const bf16x8*)(Ac); af[0][1] = *(const bf16x8*)(Ac + 32 * GLD);
; #pragma unroll
;         for (int ni = 0; ni < 4; ++ni) bfr[0][ni] = *(const bf16x8*)(Bc + ni * 32 * GLD);
;         __builtin_amdgcn_s_setprio(3);
; #pragma unroll
;         for (int ks = 0; ks < 4; ++ks) {
;             const int cb = ks & 1, nb = cb ^ 1;
;             if (ks < 3) {
;                 af[nb][0] = *(const bf16x8*)(Ac + (ks + 1) * 16); af[nb][1] = *(const bf16x8*)(Ac + 32 * GLD + (ks + 1) * 16);
; #pragma unroll
;                 for (int ni = 0; ni < 4; ++ni) bfr[nb][ni] = *(const bf16x8*)(Bc + ni * 32 * GLD + (ks + 1) * 16);
;             }
;             __builtin_amdgcn_sched_barrier(0);
; #pragma unroll
;             for (int ni = 0; ni < 4; ++ni) { acc[0][ni] = mfma32(af[cb][0], bfr[cb][ni], acc[0][ni]); acc[1][ni] = mfma32(af[cb][1], bfr[cb][ni], acc[1][ni]); }
;             __builtin_amdgcn_sched_barrier(0);
;         }
;         __builtin_amdgcn_s_setprio(0);
;         lds_barrier();
;         if (kc + 1 < nk) {
;             lstore();
;             if (kc + 2 < nk) gload(kc + 2);
;             lds_barrier();
;         }
;     }
.LBB0_678:
	s_cmp_gt_u32 s6, 14
	s_cbranch_scc1 .Lmy_gorig_2
	ds_read_b128 v[192:195], v189
	ds_read_b128 v[196:199], v189 offset:4608
	ds_read_b128 v[200:203], v190 offset:18432
	ds_read_b128 v[204:207], v190 offset:23040
	ds_read_b128 v[208:211], v190 offset:27648
	ds_read_b128 v[212:215], v190 offset:32256
	s_setprio 3
	ds_read_b128 v[216:219], v189 offset:32
	ds_read_b128 v[234:237], v189 offset:4640
	ds_read_b128 v[238:241], v190 offset:18464
	ds_read_b128 v[242:245], v190 offset:23072
	ds_read_b128 v[246:249], v190 offset:27680
	ds_read_b128 v[224:227], v190 offset:32288
	s_waitcnt lgkmcnt(9)
	v_mfma_f32_32x32x16_bf16 v[114:129], v[192:195], v[200:203], v[114:129]
	v_mfma_f32_32x32x16_bf16 v[98:113], v[196:199], v[200:203], v[98:113]
	s_waitcnt lgkmcnt(8)
	v_mfma_f32_32x32x16_bf16 v[82:97], v[192:195], v[204:207], v[82:97]
	v_mfma_f32_32x32x16_bf16 v[66:81], v[196:199], v[204:207], v[66:81]
	s_waitcnt lgkmcnt(7)
	v_mfma_f32_32x32x16_bf16 v[50:65], v[192:195], v[208:211], v[50:65]
	v_mfma_f32_32x32x16_bf16 v[34:49], v[196:199], v[208:211], v[34:49]
	s_waitcnt lgkmcnt(6)
	v_mfma_f32_32x32x16_bf16 v[18:33], v[192:195], v[212:215], v[18:33]
	v_mfma_f32_32x32x16_bf16 v[2:17], v[196:199], v[212:215], v[2:17]
	ds_read_b128 v[192:195], v189 offset:64
	ds_read_b128 v[196:199], v189 offset:4672
	ds_read_b128 v[200:203], v190 offset:18496
	ds_read_b128 v[204:207], v190 offset:23104
	ds_read_b128 v[208:211], v190 offset:27712
	ds_read_b128 v[212:215], v190 offset:32320
	s_waitcnt lgkmcnt(9)
	v_mfma_f32_32x32x16_bf16 v[114:129], v[216:219], v[238:241], v[114:129]
	v_mfma_f32_32x32x16_bf16 v[98:113], v[234:237], v[238:241], v[98:113]
	s_waitcnt lgkmcnt(8)
	v_mfma_f32_32x32x16_bf16 v[82:97], v[216:219], v[242:245], v[82:97]
	v_mfma_f32_32x32x16_bf16 v[66:81], v[234:237], v[242:245], v[66:81]
	s_waitcnt lgkmcnt(7)
	v_mfma_f32_32x32x16_bf16 v[50:65], v[216:219], v[246:249], v[50:65]
	v_mfma_f32_32x32x16_bf16 v[34:49], v[234:237], v[246:249], v[34:49]
	s_waitcnt lgkmcnt(6)
	v_mfma_f32_32x32x16_bf16 v[18:33], v[216:219], v[224:227], v[18:33]
	v_mfma_f32_32x32x16_bf16 v[2:17], v[234:237], v[224:227], v[2:17]
	ds_read_b128 v[216:219], v189 offset:96
	ds_read_b128 v[224:227], v189 offset:4704
	ds_read_b128 v[234:237], v190 offset:18528
	ds_read_b128 v[238:241], v190 offset:23136
	ds_read_b128 v[242:245], v190 offset:27744
	ds_read_b128 v[246:249], v190 offset:32352
	s_waitcnt lgkmcnt(9)
	v_mfma_f32_32x32x16_bf16 v[114:129], v[192:195], v[200:203], v[114:129]
	v_mfma_f32_32x32x16_bf16 v[98:113], v[196:199], v[200:203], v[98:113]
	s_waitcnt lgkmcnt(0)
	s_barrier
	s_setprio 0
	s_cmpk_eq_i32 s0, 0x700
	s_cbranch_scc1 .Lmy_gB_2
	v_mfma_f32_32x32x16_bf16 v[82:97], v[192:195], v[204:207], v[82:97]
	s_waitcnt vmcnt(9)
	ds_write_b128 v188, v[130:133]
	v_mfma_f32_32x32x16_bf16 v[66:81], v[196:199], v[204:207], v[66:81]
	ds_write_b128 v188, v[134:137] offset:4608
	v_mfma_f32_32x32x16_bf16 v[50:65], v[192:195], v[208:211], v[50:65]
	ds_write_b128 v188, v[138:141] offset:9216
	s_add_u32 vcc_lo, s0, 0x38a8000
	s_addc_u32 vcc_hi, s1, 0
	s_nop 0
	v_lshl_add_u64 v[130:131], v[184:185], 0, vcc
	global_load_dwordx4 v[130:133], v[130:131], off offset:256
	v_mfma_f32_32x32x16_bf16 v[34:49], v[196:199], v[208:211], v[34:49]
	s_waitcnt vmcnt(8)
	ds_write_b128 v188, v[142:145] offset:13824
	s_add_u32 vcc_lo, s0, 0x38b8000
	s_addc_u32 vcc_hi, s1, 0
	s_nop 0
	v_lshl_add_u64 v[134:135], v[184:185], 0, vcc
	global_load_dwordx4 v[134:137], v[134:135], off offset:256
	v_mfma_f32_32x32x16_bf16 v[18:33], v[192:195], v[212:215], v[18:33]
	ds_write_b128 v188, v[146:149] offset:18432
	s_add_u32 vcc_lo, s0, 0x38c8000
	s_addc_u32 vcc_hi, s1, 0
	s_nop 0
	v_lshl_add_u64 v[138:139], v[184:185], 0, vcc
	global_load_dwordx4 v[138:141], v[138:139], off offset:256
	v_mfma_f32_32x32x16_bf16 v[2:17], v[196:199], v[212:215], v[2:17]
	s_waitcnt vmcnt(9)
	ds_write_b128 v188, v[150:153] offset:23040
	s_add_u32 vcc_lo, s0, 0x38d8000
	s_addc_u32 vcc_hi, s1, 0
	s_nop 0
	v_lshl_add_u64 v[142:143], v[184:185], 0, vcc
	global_load_dwordx4 v[142:145], v[142:143], off offset:256
	v_mfma_f32_32x32x16_bf16 v[114:129], v[216:219], v[234:237], v[114:129]
	s_waitcnt vmcnt(9)
	ds_write_b128 v188, v[154:157] offset:27648
	s_add_u32 vcc_lo, s0, 0x1488000
	s_addc_u32 vcc_hi, s1, 0
	s_nop 0
	v_lshl_add_u64 v[146:147], v[182:183], 0, vcc
	global_load_dwordx4 v[146:149], v[146:147], off offset:256
	v_mfma_f32_32x32x16_bf16 v[98:113], v[224:227], v[234:237], v[98:113]
	s_waitcnt vmcnt(9)
	ds_write_b128 v188, v[158:161] offset:32256
	s_add_u32 vcc_lo, s0, 0x1498000
	s_addc_u32 vcc_hi, s1, 0
	s_nop 0
	v_lshl_add_u64 v[150:151], v[182:183], 0, vcc
	global_load_dwordx4 v[150:153], v[150:151], off offset:256
	v_mfma_f32_32x32x16_bf16 v[82:97], v[216:219], v[238:241], v[82:97]
	s_waitcnt vmcnt(9)
	ds_write_b128 v188, v[162:165] offset:36864
	s_add_u32 vcc_lo, s0, 0x14a8000
	s_addc_u32 vcc_hi, s1, 0
	s_nop 0
	v_lshl_add_u64 v[154:155], v[182:183], 0, vcc
	global_load_dwordx4 v[154:157], v[154:155], off offset:256
	v_mfma_f32_32x32x16_bf16 v[66:81], v[224:227], v[238:241], v[66:81]
	s_waitcnt vmcnt(9)
	ds_write_b128 v188, v[166:169] offset:41472
	s_add_u32 vcc_lo, s0, 0x14b8000
	s_addc_u32 vcc_hi, s1, 0
	s_nop 0
	v_lshl_add_u64 v[158:159], v[182:183], 0, vcc
	global_load_dwordx4 v[158:161], v[158:159], off offset:256
	v_mfma_f32_32x32x16_bf16 v[50:65], v[216:219], v[242:245], v[50:65]
	s_waitcnt vmcnt(9)
	ds_write_b128 v188, v[170:173] offset:46080
	s_add_u32 vcc_lo, s0, 0x14c8000
	s_addc_u32 vcc_hi, s1, 0
	s_nop 0
	v_lshl_add_u64 v[162:163], v[182:183], 0, vcc
	global_load_dwordx4 v[162:165], v[162:163], off offset:256
	v_mfma_f32_32x32x16_bf16 v[34:49], v[224:227], v[242:245], v[34:49]
	s_waitcnt vmcnt(9)
	ds_write_b128 v188, v[174:177] offset:50688
	s_add_u32 vcc_lo, s0, 0x14d8000
	s_addc_u32 vcc_hi, s1, 0
	s_nop 0
	v_lshl_add_u64 v[166:167], v[182:183], 0, vcc
	global_load_dwordx4 v[166:169], v[166:167], off offset:256
	v_mfma_f32_32x32x16_bf16 v[18:33], v[216:219], v[246:249], v[18:33]
	s_add_u32 vcc_lo, s0, 0x14e8000
	s_addc_u32 vcc_hi, s1, 0
	s_nop 0
	v_lshl_add_u64 v[170:171], v[182:183], 0, vcc
	global_load_dwordx4 v[170:173], v[170:171], off offset:256
	v_mfma_f32_32x32x16_bf16 v[2:17], v[224:227], v[246:249], v[2:17]
	s_add_u32 vcc_lo, s0, 0x14f8000
	s_addc_u32 vcc_hi, s1, 0
	s_nop 0
	v_lshl_add_u64 v[174:175], v[182:183], 0, vcc
	global_load_dwordx4 v[174:177], v[174:175], off offset:256
	s_branch .LBB0_676
; __device__ __forceinline__ void lds_barrier() { asm volatile("s_waitcnt lgkmcnt(0)\n\ts_barrier" ::: "memory"); }
; __device__ __forceinline__ void gemm_big(const bf16_t* __restrict__ A, long lda, const bf16_t* __restrict__ Bt, int K, f32x16 (&acc)[2][4], unsigned char* lds) {
;     ...
;         lds_barrier();
;         if (kc + 1 < nk) {
;             lstore();
;             if (kc + 2 < nk) gload(kc + 2);
;             lds_barrier();
.Lmy_gB_2:
	v_mfma_f32_32x32x16_bf16 v[82:97], v[192:195], v[204:207], v[82:97]
	s_waitcnt vmcnt(9)
	ds_write_b128 v188, v[130:133]
	v_mfma_f32_32x32x16_bf16 v[66:81], v[196:199], v[204:207], v[66:81]
	ds_write_b128 v188, v[134:137] offset:4608
	v_mfma_f32_32x32x16_bf16 v[50:65], v[192:195], v[208:211], v[50:65]
	ds_write_b128 v188, v[138:141] offset:9216
	v_mfma_f32_32x32x16_bf16 v[34:49], v[196:199], v[208:211], v[34:49]
	s_waitcnt vmcnt(7)
	ds_write_b128 v188, v[142:145] offset:13824
	v_mfma_f32_32x32x16_bf16 v[18:33], v[192:195], v[212:215], v[18:33]
	ds_write_b128 v188, v[146:149] offset:18432
	v_mfma_f32_32x32x16_bf16 v[2:17], v[196:199], v[212:215], v[2:17]
	s_waitcnt vmcnt(6)
	ds_write_b128 v188, v[150:153] offset:23040
	v_mfma_f32_32x32x16_bf16 v[114:129], v[216:219], v[234:237], v[114:129]
	s_waitcnt vmcnt(5)
	ds_write_b128 v188, v[154:157] offset:27648
	v_mfma_f32_32x32x16_bf16 v[98:113], v[224:227], v[234:237], v[98:113]
	s_waitcnt vmcnt(4)
	ds_write_b128 v188, v[158:161] offset:32256
	v_mfma_f32_32x32x16_bf16 v[82:97], v[216:219], v[238:241], v[82:97]
	s_waitcnt vmcnt(3)
	ds_write_b128 v188, v[162:165] offset:36864
	v_mfma_f32_32x32x16_bf16 v[66:81], v[224:227], v[238:241], v[66:81]
	s_waitcnt vmcnt(2)
	ds_write_b128 v188, v[166:169] offset:41472
	v_mfma_f32_32x32x16_bf16 v[50:65], v[216:219], v[242:245], v[50:65]
	s_waitcnt vmcnt(1)
	ds_write_b128 v188, v[170:173] offset:46080
	v_mfma_f32_32x32x16_bf16 v[34:49], v[224:227], v[242:245], v[34:49]
	s_waitcnt vmcnt(0)
	ds_write_b128 v188, v[174:177] offset:50688
	v_mfma_f32_32x32x16_bf16 v[18:33], v[216:219], v[246:249], v[18:33]
	v_mfma_f32_32x32x16_bf16 v[2:17], v[224:227], v[246:249], v[2:17]
	s_branch .LBB0_676

; __device__ __forceinline__ void lds_barrier() { asm volatile("s_waitcnt lgkmcnt(0)\n\ts_barrier" ::: "memory"); }
; __device__ __forceinline__ f32x16 mfma32(bf16x8 a, bf16x8 b, f32x16 c) { return __builtin_amdgcn_mfma_f32_32x32x16_bf16(a, b, c, 0, 0, 0); }
; __device__ __forceinline__ void gemm_big(const bf16_t* __restrict__ A, long lda, const bf16_t* __restrict__ Bt, int K, f32x16 (&acc)[2][4], unsigned char* lds) {
;     ...
;     for (int kc = 0; kc < nk; ++kc) {
;         bf16x8 af[2][2], bfr[2][4];
;         af[0][0] = *(const bf16x8*)(Ac); af[0][1] = *(const bf16x8*)(Ac + 32 * GLD);
; #pragma unroll
;         for (int ni = 0; ni < 4; ++ni) bfr[0][ni] = *(const bf16x8*)(Bc + ni * 32 * GLD);
;         __builtin_amdgcn_s_setprio(3);
; #pragma unroll
;         for (int ks = 0; ks < 4; ++ks) {
;             const int cb = ks & 1, nb = cb ^ 1;
;             if (ks < 3) {
;                 af[nb][0] = *(const bf16x8*)(Ac + (ks + 1) * 16); af[nb][1] = *(const bf16x8*)(Ac + 32 * GLD + (ks + 1) * 16);
; #pragma unroll
;                 for (int ni = 0; ni < 4; ++ni) bfr[nb][ni] = *(const bf16x8*)(Bc + ni * 32 * GLD + (ks + 1) * 16);
;             }
;             __builtin_amdgcn_sched_barrier(0);
; #pragma unroll
;             for (int ni = 0; ni < 4; ++ni) { acc[0][ni] = mfma32(af[cb][0], bfr[cb][ni], acc[0][ni]); acc[1][ni] = mfma32(af[cb][1], bfr[cb][ni], acc[1][ni]); }
;             __builtin_amdgcn_sched_barrier(0);
;         }
;         __builtin_amdgcn_s_setprio(0);
;         lds_barrier();
;         if (kc + 1 < nk) {
;             lstore();
;             if (kc + 2 < nk) gload(kc + 2);
;             lds_barrier();
;         }
;     }
; __device__ __forceinline__ void phase_resid(const Params& p, const bf16_t* A, long lda, int mrows, const bf16_t* Bt, int K, float* xres, float scale, unsigned char* lds) {
;     ...
;         gemm_big(A + (size_t)pm * 128 * lda, lda, Bt + (size_t)pn * 256 * K, K, acc, lds);
.LBB0_775:
	s_cmp_gt_u32 s14, 42
	s_cbranch_scc1 .Lmy_gorig_1
	ds_read_b128 v[190:193], v187
	ds_read_b128 v[194:197], v187 offset:4608
	ds_read_b128 v[198:201], v188 offset:18432
	ds_read_b128 v[202:205], v188 offset:23040
	ds_read_b128 v[206:209], v188 offset:27648
	ds_read_b128 v[210:213], v188 offset:32256
	s_setprio 3
	ds_read_b128 v[214:217], v187 offset:32
	ds_read_b128 v[218:221], v187 offset:4640
	ds_read_b128 v[234:237], v188 offset:18464
	ds_read_b128 v[238:241], v188 offset:23072
	ds_read_b128 v[242:245], v188 offset:27680
	ds_read_b128 v[246:249], v188 offset:32288
	s_waitcnt lgkmcnt(9)
	v_mfma_f32_32x32x16_bf16 v[114:129], v[190:193], v[198:201], v[114:129]
	v_mfma_f32_32x32x16_bf16 v[50:65], v[194:197], v[198:201], v[50:65]
	s_waitcnt lgkmcnt(8)
	v_mfma_f32_32x32x16_bf16 v[98:113], v[190:193], v[202:205], v[98:113]
	v_mfma_f32_32x32x16_bf16 v[34:49], v[194:197], v[202:205], v[34:49]
	s_waitcnt lgkmcnt(7)
	v_mfma_f32_32x32x16_bf16 v[82:97], v[190:193], v[206:209], v[82:97]
	v_mfma_f32_32x32x16_bf16 v[18:33], v[194:197], v[206:209], v[18:33]
	s_waitcnt lgkmcnt(6)
	v_mfma_f32_32x32x16_bf16 v[66:81], v[190:193], v[210:213], v[66:81]
	v_mfma_f32_32x32x16_bf16 v[2:17], v[194:197], v[210:213], v[2:17]
	ds_read_b128 v[190:193], v187 offset:64
	ds_read_b128 v[194:197], v187 offset:4672
	ds_read_b128 v[198:201], v188 offset:18496
	ds_read_b128 v[202:205], v188 offset:23104
	ds_read_b128 v[206:209], v188 offset:27712
	ds_read_b128 v[210:213], v188 offset:32320
	s_waitcnt lgkmcnt(9)
	v_mfma_f32_32x32x16_bf16 v[114:129], v[214:217], v[234:237], v[114:129]
	v_mfma_f32_32x32x16_bf16 v[50:65], v[218:221], v[234:237], v[50:65]
	s_waitcnt lgkmcnt(8)
	v_mfma_f32_32x32x16_bf16 v[98:113], v[214:217], v[238:241], v[98:113]
	v_mfma_f32_32x32x16_bf16 v[34:49], v[218:221], v[238:241], v[34:49]
	s_waitcnt lgkmcnt(7)
	v_mfma_f32_32x32x16_bf16 v[82:97], v[214:217], v[242:245], v[82:97]
	v_mfma_f32_32x32x16_bf16 v[18:33], v[218:221], v[242:245], v[18:33]
	s_waitcnt lgkmcnt(6)
	v_mfma_f32_32x32x16_bf16 v[66:81], v[214:217], v[246:249], v[66:81]
	v_mfma_f32_32x32x16_bf16 v[2:17], v[218:221], v[246:249], v[2:17]
	ds_read_b128 v[214:217], v187 offset:96
	ds_read_b128 v[218:221], v187 offset:4704
	ds_read_b128 v[234:237], v188 offset:18528
	ds_read_b128 v[238:241], v188 offset:23136
	ds_read_b128 v[242:245], v188 offset:27744
	ds_read_b128 v[246:249], v188 offset:32352
	s_waitcnt lgkmcnt(9)
	v_mfma_f32_32x32x16_bf16 v[114:129], v[190:193], v[198:201], v[114:129]
	v_mfma_f32_32x32x16_bf16 v[50:65], v[194:197], v[198:201], v[50:65]
	s_waitcnt lgkmcnt(0)
	s_barrier
	s_setprio 0
	s_cmpk_eq_i32 s4, 0x1500
	s_cbranch_scc1 .Lmy_gB_1
	v_mfma_f32_32x32x16_bf16 v[98:113], v[190:193], v[202:205], v[98:113]
	s_waitcnt vmcnt(9)
	ds_write_b128 v189, v[130:133]
	v_mfma_f32_32x32x16_bf16 v[34:49], v[194:197], v[202:205], v[34:49]
	ds_write_b128 v189, v[134:137] offset:4608
	v_mfma_f32_32x32x16_bf16 v[82:97], v[190:193], v[206:209], v[82:97]
	ds_write_b128 v189, v[138:141] offset:9216
	s_add_u32 vcc_lo, s4, 0x78a8000
	s_addc_u32 vcc_hi, s5, 0
	s_nop 0
	v_lshl_add_u64 v[130:131], v[184:185], 0, vcc
	global_load_dwordx4 v[130:133], v[130:131], off offset:256
	v_mfma_f32_32x32x16_bf16 v[18:33], v[194:197], v[206:209], v[18:33]
	s_waitcnt vmcnt(8)
	ds_write_b128 v189, v[142:145] offset:13824
	s_add_u32 vcc_lo, s4, 0x78d4000
	s_addc_u32 vcc_hi, s5, 0
	s_nop 0
	v_lshl_add_u64 v[134:135], v[184:185], 0, vcc
	global_load_dwordx4 v[134:137], v[134:135], off offset:256
	v_mfma_f32_32x32x16_bf16 v[66:81], v[190:193], v[210:213], v[66:81]
	ds_write_b128 v189, v[146:149] offset:18432
	s_add_u32 vcc_lo, s4, 0x7900000
	s_addc_u32 vcc_hi, s5, 0
	s_nop 0
	v_lshl_add_u64 v[138:139], v[184:185], 0, vcc
	global_load_dwordx4 v[138:141], v[138:139], off offset:256
	v_mfma_f32_32x32x16_bf16 v[2:17], v[194:197], v[210:213], v[2:17]
	s_waitcnt vmcnt(9)
	ds_write_b128 v189, v[150:153] offset:23040
	s_add_u32 vcc_lo, s4, 0x792c000
	s_addc_u32 vcc_hi, s5, 0
	s_nop 0
	v_lshl_add_u64 v[142:143], v[184:185], 0, vcc
	global_load_dwordx4 v[142:145], v[142:143], off offset:256
	v_mfma_f32_32x32x16_bf16 v[114:129], v[214:217], v[234:237], v[114:129]
	s_waitcnt vmcnt(9)
	ds_write_b128 v189, v[154:157] offset:27648
	s_add_u32 vcc_lo, s4, 0xf08000
	s_addc_u32 vcc_hi, s5, 0
	s_nop 0
	v_lshl_add_u64 v[146:147], v[182:183], 0, vcc
	global_load_dwordx4 v[146:149], v[146:147], off offset:256
	v_mfma_f32_32x32x16_bf16 v[50:65], v[218:221], v[234:237], v[50:65]
	s_waitcnt vmcnt(9)
	ds_write_b128 v189, v[158:161] offset:32256
	s_add_u32 vcc_lo, s4, 0xf34000
	s_addc_u32 vcc_hi, s5, 0
	s_nop 0
	v_lshl_add_u64 v[150:151], v[182:183], 0, vcc
	global_load_dwordx4 v[150:153], v[150:151], off offset:256
	v_mfma_f32_32x32x16_bf16 v[98:113], v[214:217], v[238:241], v[98:113]
	s_waitcnt vmcnt(9)
	ds_write_b128 v189, v[162:165] offset:36864
	s_add_u32 vcc_lo, s4, 0xf60000
	s_addc_u32 vcc_hi, s5, 0
	s_nop 0
	v_lshl_add_u64 v[154:155], v[182:183], 0, vcc
	global_load_dwordx4 v[154:157], v[154:155], off offset:256
	v_mfma_f32_32x32x16_bf16 v[34:49], v[218:221], v[238:241], v[34:49]
	s_waitcnt vmcnt(9)
	ds_write_b128 v189, v[166:169] offset:41472
	s_add_u32 vcc_lo, s4, 0xf8c000
	s_addc_u32 vcc_hi, s5, 0
	s_nop 0
	v_lshl_add_u64 v[158:159], v[182:183], 0, vcc
	global_load_dwordx4 v[158:161], v[158:159], off offset:256
	v_mfma_f32_32x32x16_bf16 v[82:97], v[214:217], v[242:245], v[82:97]
	s_waitcnt vmcnt(9)
	ds_write_b128 v189, v[170:173] offset:46080
	s_add_u32 vcc_lo, s4, 0xfb8000
	s_addc_u32 vcc_hi, s5, 0
	s_nop 0
	v_lshl_add_u64 v[162:163], v[182:183], 0, vcc
	global_load_dwordx4 v[162:165], v[162:163], off offset:256
	v_mfma_f32_32x32x16_bf16 v[18:33], v[218:221], v[242:245], v[18:33]
	s_waitcnt vmcnt(9)
	ds_write_b128 v189, v[174:177] offset:50688
	s_add_u32 vcc_lo, s4, 0xfe4000
	s_addc_u32 vcc_hi, s5, 0
	s_nop 0
	v_lshl_add_u64 v[166:167], v[182:183], 0, vcc
	global_load_dwordx4 v[166:169], v[166:167], off offset:256
	v_mfma_f32_32x32x16_bf16 v[66:81], v[214:217], v[246:249], v[66:81]
	s_add_u32 vcc_lo, s4, 0x1010000
	s_addc_u32 vcc_hi, s5, 0
	s_nop 0
	v_lshl_add_u64 v[170:171], v[182:183], 0, vcc
	global_load_dwordx4 v[170:173], v[170:171], off offset:256
	v_mfma_f32_32x32x16_bf16 v[2:17], v[218:221], v[246:249], v[2:17]
	s_add_u32 vcc_lo, s4, 0x103c000
	s_addc_u32 vcc_hi, s5, 0
	s_nop 0
	v_lshl_add_u64 v[174:175], v[182:183], 0, vcc
	global_load_dwordx4 v[174:177], v[174:175], off offset:256
	s_branch .LBB0_773
; __device__ __forceinline__ void lds_barrier() { asm volatile("s_waitcnt lgkmcnt(0)\n\ts_barrier" ::: "memory"); }
; __device__ __forceinline__ void gemm_big(const bf16_t* __restrict__ A, long lda, const bf16_t* __restrict__ Bt, int K, f32x16 (&acc)[2][4], unsigned char* lds) {
;     ...
;         lds_barrier();
;         if (kc + 1 < nk) {
;             lstore();
;             if (kc + 2 < nk) gload(kc + 2);
;             lds_barrier();
.Lmy_gB_1:
	v_mfma_f32_32x32x16_bf16 v[98:113], v[190:193], v[202:205], v[98:113]
	s_waitcnt vmcnt(9)
	ds_write_b128 v189, v[130:133]
	v_mfma_f32_32x32x16_bf16 v[34:49], v[194:197], v[202:205], v[34:49]
	ds_write_b128 v189, v[134:137] offset:4608
	v_mfma_f32_32x32x16_bf16 v[82:97], v[190:193], v[206:209], v[82:97]
	ds_write_b128 v189, v[138:141] offset:9216
	v_mfma_f32_32x32x16_bf16 v[18:33], v[194:197], v[206:209], v[18:33]
	s_waitcnt vmcnt(7)
	ds_write_b128 v189, v[142:145] offset:13824
	v_mfma_f32_32x32x16_bf16 v[66:81], v[190:193], v[210:213], v[66:81]
	ds_write_b128 v189, v[146:149] offset:18432
	v_mfma_f32_32x32x16_bf16 v[2:17], v[194:197], v[210:213], v[2:17]
	s_waitcnt vmcnt(6)
	ds_write_b128 v189, v[150:153] offset:23040
	v_mfma_f32_32x32x16_bf16 v[114:129], v[214:217], v[234:237], v[114:129]
	s_waitcnt vmcnt(5)
	ds_write_b128 v189, v[154:157] offset:27648
	v_mfma_f32_32x32x16_bf16 v[50:65], v[218:221], v[234:237], v[50:65]
	s_waitcnt vmcnt(4)
	ds_write_b128 v189, v[158:161] offset:32256
	v_mfma_f32_32x32x16_bf16 v[98:113], v[214:217], v[238:241], v[98:113]
	s_waitcnt vmcnt(3)
	ds_write_b128 v189, v[162:165] offset:36864
	v_mfma_f32_32x32x16_bf16 v[34:49], v[218:221], v[238:241], v[34:49]
	s_waitcnt vmcnt(2)
	ds_write_b128 v189, v[166:169] offset:41472
	v_mfma_f32_32x32x16_bf16 v[82:97], v[214:217], v[242:245], v[82:97]
	s_waitcnt vmcnt(1)
	ds_write_b128 v189, v[170:173] offset:46080
	v_mfma_f32_32x32x16_bf16 v[18:33], v[218:221], v[242:245], v[18:33]
	s_waitcnt vmcnt(0)
	ds_write_b128 v189, v[174:177] offset:50688
	v_mfma_f32_32x32x16_bf16 v[66:81], v[214:217], v[246:249], v[66:81]
	v_mfma_f32_32x32x16_bf16 v[2:17], v[218:221], v[246:249], v[2:17]
	s_branch .LBB0_773

; __device__ __forceinline__ void lds_barrier() { asm volatile("s_waitcnt lgkmcnt(0)\n\ts_barrier" ::: "memory"); }
; __device__ __forceinline__ f32x16 mfma32(bf16x8 a, bf16x8 b, f32x16 c) { return __builtin_amdgcn_mfma_f32_32x32x16_bf16(a, b, c, 0, 0, 0); }
; __device__ __forceinline__ void gemm_big(const bf16_t* __restrict__ A, long lda, const bf16_t* __restrict__ Bt, int K, f32x16 (&acc)[2][4], unsigned char* lds) {
;     ...
;     for (int kc = 0; kc < nk; ++kc) {
;         bf16x8 af[2][2], bfr[2][4];
;         af[0][0] = *(const bf16x8*)(Ac); af[0][1] = *(const bf16x8*)(Ac + 32 * GLD);
; #pragma unroll
;         for (int ni = 0; ni < 4; ++ni) bfr[0][ni] = *(const bf16x8*)(Bc + ni * 32 * GLD);
;         __builtin_amdgcn_s_setprio(3);
; #pragma unroll
;         for (int ks = 0; ks < 4; ++ks) {
;             const int cb = ks & 1, nb = cb ^ 1;
;             if (ks < 3) {
;                 af[nb][0] = *(const bf16x8*)(Ac + (ks + 1) * 16); af[nb][1] = *(const bf16x8*)(Ac + 32 * GLD + (ks + 1) * 16);
; #pragma unroll
;                 for (int ni = 0; ni < 4; ++ni) bfr[nb][ni] = *(const bf16x8*)(Bc + ni * 32 * GLD + (ks + 1) * 16);
;             }
;             __builtin_amdgcn_sched_barrier(0);
; #pragma unroll
;             for (int ni = 0; ni < 4; ++ni) { acc[0][ni] = mfma32(af[cb][0], bfr[cb][ni], acc[0][ni]); acc[1][ni] = mfma32(af[cb][1], bfr[cb][ni], acc[1][ni]); }
;             __builtin_amdgcn_sched_barrier(0);
;         }
;         __builtin_amdgcn_s_setprio(0);
;         lds_barrier();
;         if (kc + 1 < nk) {
;             lstore();
;             if (kc + 2 < nk) gload(kc + 2);
;             lds_barrier();
;         }
;     }
.LBB0_788:
	s_cmp_gt_u32 s5, 14
	s_cbranch_scc1 .Lmy_gorig_0
	ds_read_b128 v[190:193], v188
	ds_read_b128 v[194:197], v188 offset:4608
	ds_read_b128 v[198:201], v189 offset:18432
	ds_read_b128 v[202:205], v189 offset:23040
	ds_read_b128 v[206:209], v189 offset:27648
	ds_read_b128 v[210:213], v189 offset:32256
	s_setprio 3
	ds_read_b128 v[214:217], v188 offset:32
	ds_read_b128 v[234:237], v188 offset:4640
	ds_read_b128 v[238:241], v189 offset:18464
	ds_read_b128 v[242:245], v189 offset:23072
	ds_read_b128 v[246:249], v189 offset:27680
	ds_read_b128 v[218:221], v189 offset:32288
	s_waitcnt lgkmcnt(9)
	v_mfma_f32_32x32x16_bf16 v[114:129], v[190:193], v[198:201], v[114:129]
	v_mfma_f32_32x32x16_bf16 v[82:97], v[194:197], v[198:201], v[82:97]
	s_waitcnt lgkmcnt(8)
	v_mfma_f32_32x32x16_bf16 v[98:113], v[190:193], v[202:205], v[98:113]
	v_mfma_f32_32x32x16_bf16 v[66:81], v[194:197], v[202:205], v[66:81]
	s_waitcnt lgkmcnt(7)
	v_mfma_f32_32x32x16_bf16 v[50:65], v[190:193], v[206:209], v[50:65]
	v_mfma_f32_32x32x16_bf16 v[18:33], v[194:197], v[206:209], v[18:33]
	s_waitcnt lgkmcnt(6)
	v_mfma_f32_32x32x16_bf16 v[34:49], v[190:193], v[210:213], v[34:49]
	v_mfma_f32_32x32x16_bf16 v[2:17], v[194:197], v[210:213], v[2:17]
	ds_read_b128 v[190:193], v188 offset:64
	ds_read_b128 v[194:197], v188 offset:4672
	ds_read_b128 v[198:201], v189 offset:18496
	ds_read_b128 v[202:205], v189 offset:23104
	ds_read_b128 v[206:209], v189 offset:27712
	ds_read_b128 v[210:213], v189 offset:32320
	s_waitcnt lgkmcnt(9)
	v_mfma_f32_32x32x16_bf16 v[114:129], v[214:217], v[238:241], v[114:129]
	v_mfma_f32_32x32x16_bf16 v[82:97], v[234:237], v[238:241], v[82:97]
	s_waitcnt lgkmcnt(8)
	v_mfma_f32_32x32x16_bf16 v[98:113], v[214:217], v[242:245], v[98:113]
	v_mfma_f32_32x32x16_bf16 v[66:81], v[234:237], v[242:245], v[66:81]
	s_waitcnt lgkmcnt(7)
	v_mfma_f32_32x32x16_bf16 v[50:65], v[214:217], v[246:249], v[50:65]
	v_mfma_f32_32x32x16_bf16 v[18:33], v[234:237], v[246:249], v[18:33]
	s_waitcnt lgkmcnt(6)
	v_mfma_f32_32x32x16_bf16 v[34:49], v[214:217], v[218:221], v[34:49]
	v_mfma_f32_32x32x16_bf16 v[2:17], v[234:237], v[218:221], v[2:17]
	ds_read_b128 v[214:217], v188 offset:96
	ds_read_b128 v[218:221], v188 offset:4704
	ds_read_b128 v[234:237], v189 offset:18528
	ds_read_b128 v[238:241], v189 offset:23136
	ds_read_b128 v[242:245], v189 offset:27744
	ds_read_b128 v[246:249], v189 offset:32352
	s_waitcnt lgkmcnt(9)
	v_mfma_f32_32x32x16_bf16 v[114:129], v[190:193], v[198:201], v[114:129]
	v_mfma_f32_32x32x16_bf16 v[82:97], v[194:197], v[198:201], v[82:97]
	s_waitcnt lgkmcnt(0)
	s_barrier
	s_setprio 0
	s_cmpk_eq_i32 s6, 0x700
	s_cbranch_scc1 .Lmy_gB_0
	v_mfma_f32_32x32x16_bf16 v[98:113], v[190:193], v[202:205], v[98:113]
	s_waitcnt vmcnt(9)
	ds_write_b128 v187, v[130:133]
	v_mfma_f32_32x32x16_bf16 v[66:81], v[194:197], v[202:205], v[66:81]
	ds_write_b128 v187, v[134:137] offset:4608
	v_mfma_f32_32x32x16_bf16 v[50:65], v[190:193], v[206:209], v[50:65]
	ds_write_b128 v187, v[138:141] offset:9216
	s_add_u32 vcc_lo, s6, 0x38a8000
	s_addc_u32 vcc_hi, s7, 0
	s_nop 0
	v_lshl_add_u64 v[130:131], v[184:185], 0, vcc
	global_load_dwordx4 v[130:133], v[130:131], off offset:256
	v_mfma_f32_32x32x16_bf16 v[18:33], v[194:197], v[206:209], v[18:33]
	s_waitcnt vmcnt(8)
	ds_write_b128 v187, v[142:145] offset:13824
	s_add_u32 vcc_lo, s6, 0x38b8000
	s_addc_u32 vcc_hi, s7, 0
	s_nop 0
	v_lshl_add_u64 v[134:135], v[184:185], 0, vcc
	global_load_dwordx4 v[134:137], v[134:135], off offset:256
	v_mfma_f32_32x32x16_bf16 v[34:49], v[190:193], v[210:213], v[34:49]
	ds_write_b128 v187, v[146:149] offset:18432
	s_add_u32 vcc_lo, s6, 0x38c8000
	s_addc_u32 vcc_hi, s7, 0
	s_nop 0
	v_lshl_add_u64 v[138:139], v[184:185], 0, vcc
	global_load_dwordx4 v[138:141], v[138:139], off offset:256
	v_mfma_f32_32x32x16_bf16 v[2:17], v[194:197], v[210:213], v[2:17]
	s_waitcnt vmcnt(9)
	ds_write_b128 v187, v[150:153] offset:23040
	s_add_u32 vcc_lo, s6, 0x38d8000
	s_addc_u32 vcc_hi, s7, 0
	s_nop 0
	v_lshl_add_u64 v[142:143], v[184:185], 0, vcc
	global_load_dwordx4 v[142:145], v[142:143], off offset:256
	v_mfma_f32_32x32x16_bf16 v[114:129], v[214:217], v[234:237], v[114:129]
	s_waitcnt vmcnt(9)
	ds_write_b128 v187, v[154:157] offset:27648
	s_add_u32 vcc_lo, s6, 0x408000
	s_addc_u32 vcc_hi, s7, 0
	s_nop 0
	v_lshl_add_u64 v[146:147], v[182:183], 0, vcc
	global_load_dwordx4 v[146:149], v[146:147], off offset:256
	v_mfma_f32_32x32x16_bf16 v[82:97], v[218:221], v[234:237], v[82:97]
	s_waitcnt vmcnt(9)
	ds_write_b128 v187, v[158:161] offset:32256
	s_add_u32 vcc_lo, s6, 0x418000
	s_addc_u32 vcc_hi, s7, 0
	s_nop 0
	v_lshl_add_u64 v[150:151], v[182:183], 0, vcc
	global_load_dwordx4 v[150:153], v[150:151], off offset:256
	v_mfma_f32_32x32x16_bf16 v[98:113], v[214:217], v[238:241], v[98:113]
	s_waitcnt vmcnt(9)
	ds_write_b128 v187, v[162:165] offset:36864
	s_add_u32 vcc_lo, s6, 0x428000
	s_addc_u32 vcc_hi, s7, 0
	s_nop 0
	v_lshl_add_u64 v[154:155], v[182:183], 0, vcc
	global_load_dwordx4 v[154:157], v[154:155], off offset:256
	v_mfma_f32_32x32x16_bf16 v[66:81], v[218:221], v[238:241], v[66:81]
	s_waitcnt vmcnt(9)
	ds_write_b128 v187, v[166:169] offset:41472
	s_add_u32 vcc_lo, s6, 0x438000
	s_addc_u32 vcc_hi, s7, 0
	s_nop 0
	v_lshl_add_u64 v[158:159], v[182:183], 0, vcc
	global_load_dwordx4 v[158:161], v[158:159], off offset:256
	v_mfma_f32_32x32x16_bf16 v[50:65], v[214:217], v[242:245], v[50:65]
	s_waitcnt vmcnt(9)
	ds_write_b128 v187, v[170:173] offset:46080
	s_add_u32 vcc_lo, s6, 0x448000
	s_addc_u32 vcc_hi, s7, 0
	s_nop 0
	v_lshl_add_u64 v[162:163], v[182:183], 0, vcc
	global_load_dwordx4 v[162:165], v[162:163], off offset:256
	v_mfma_f32_32x32x16_bf16 v[18:33], v[218:221], v[242:245], v[18:33]
	s_waitcnt vmcnt(9)
	ds_write_b128 v187, v[174:177] offset:50688
	s_add_u32 vcc_lo, s6, 0x458000
	s_addc_u32 vcc_hi, s7, 0
	s_nop 0
	v_lshl_add_u64 v[166:167], v[182:183], 0, vcc
	global_load_dwordx4 v[166:169], v[166:167], off offset:256
	v_mfma_f32_32x32x16_bf16 v[34:49], v[214:217], v[246:249], v[34:49]
	s_add_u32 vcc_lo, s6, 0x468000
	s_addc_u32 vcc_hi, s7, 0
	s_nop 0
	v_lshl_add_u64 v[170:171], v[182:183], 0, vcc
	global_load_dwordx4 v[170:173], v[170:171], off offset:256
	v_mfma_f32_32x32x16_bf16 v[2:17], v[218:221], v[246:249], v[2:17]
	s_add_u32 vcc_lo, s6, 0x478000
	s_addc_u32 vcc_hi, s7, 0
	s_nop 0
	v_lshl_add_u64 v[174:175], v[182:183], 0, vcc
	global_load_dwordx4 v[174:177], v[174:175], off offset:256
	s_branch .LBB0_786
; __device__ __forceinline__ void lds_barrier() { asm volatile("s_waitcnt lgkmcnt(0)\n\ts_barrier" ::: "memory"); }
; __device__ __forceinline__ void gemm_big(const bf16_t* __restrict__ A, long lda, const bf16_t* __restrict__ Bt, int K, f32x16 (&acc)[2][4], unsigned char* lds) {
;     ...
;         lds_barrier();
;         if (kc + 1 < nk) {
;             lstore();
;             if (kc + 2 < nk) gload(kc + 2);
;             lds_barrier();
.Lmy_gB_0:
	v_mfma_f32_32x32x16_bf16 v[98:113], v[190:193], v[202:205], v[98:113]
	s_waitcnt vmcnt(9)
	ds_write_b128 v187, v[130:133]
	v_mfma_f32_32x32x16_bf16 v[66:81], v[194:197], v[202:205], v[66:81]
	ds_write_b128 v187, v[134:137] offset:4608
	v_mfma_f32_32x32x16_bf16 v[50:65], v[190:193], v[206:209], v[50:65]
	ds_write_b128 v187, v[138:141] offset:9216
	v_mfma_f32_32x32x16_bf16 v[18:33], v[194:197], v[206:209], v[18:33]
	s_waitcnt vmcnt(7)
	ds_write_b128 v187, v[142:145] offset:13824
	v_mfma_f32_32x32x16_bf16 v[34:49], v[190:193], v[210:213], v[34:49]
	ds_write_b128 v187, v[146:149] offset:18432
	v_mfma_f32_32x32x16_bf16 v[2:17], v[194:197], v[210:213], v[2:17]
	s_waitcnt vmcnt(6)
	ds_write_b128 v187, v[150:153] offset:23040
	v_mfma_f32_32x32x16_bf16 v[114:129], v[214:217], v[234:237], v[114:129]
	s_waitcnt vmcnt(5)
	ds_write_b128 v187, v[154:157] offset:27648
	v_mfma_f32_32x32x16_bf16 v[82:97], v[218:221], v[234:237], v[82:97]
	s_waitcnt vmcnt(4)
	ds_write_b128 v187, v[158:161] offset:32256
	v_mfma_f32_32x32x16_bf16 v[98:113], v[214:217], v[238:241], v[98:113]
	s_waitcnt vmcnt(3)
	ds_write_b128 v187, v[162:165] offset:36864
	v_mfma_f32_32x32x16_bf16 v[66:81], v[218:221], v[238:241], v[66:81]
	s_waitcnt vmcnt(2)
	ds_write_b128 v187, v[166:169] offset:41472
	v_mfma_f32_32x32x16_bf16 v[50:65], v[214:217], v[242:245], v[50:65]
	s_waitcnt vmcnt(1)
	ds_write_b128 v187, v[170:173] offset:46080
	v_mfma_f32_32x32x16_bf16 v[18:33], v[218:221], v[242:245], v[18:33]
	s_waitcnt vmcnt(0)
	ds_write_b128 v187, v[174:177] offset:50688
	v_mfma_f32_32x32x16_bf16 v[34:49], v[214:217], v[246:249], v[34:49]
	v_mfma_f32_32x32x16_bf16 v[2:17], v[218:221], v[246:249], v[2:17]
	s_branch .LBB0_786
